# stw
# speedup vs baseline: 1.0256x; 1.0245x over previous
; #define PU_LOAD_A(ID, tt) { _Pragma("unroll") for (int i = 0; i < 4; ++i) ID[i] = *(const int4*)(selE + (size_t)(tt) * 128 + sub * 16 + 4 * i); }
; __device__ void phase_pu(const Params& p, const XcdBarrier& xb) {
;     ...
;   const int wrank = __builtin_amdgcn_readfirstlane((int)xb.rank) * 4 + w;
;   const int nw = __builtin_amdgcn_readfirstlane((int)xb.nloc) * 4;
;   const int nx = __builtin_amdgcn_readfirstlane((int)xb.nx);
;   const int xi = __builtin_amdgcn_readfirstlane((int)xb.xi);
;   u32x4 u0[16], u1[16], xa0, xb0, xa1, xb1;
;   int4 id_n[4], id_nn[4];
;   int s_c = xi, t_c = wrank;
;   int s_n = s_c, t_n = t_c + nw; if (t_n >= T) { t_n = wrank; s_n += nx; }
;   int s_nn = s_n, t_nn = t_n + nw; if (t_nn >= T) { t_nn = wrank; s_nn += nx; }
;     ...
;   if (s_c < 8) {
;     {
;       int4 id_c[4];
;       PU_LOAD_A(id_c, t_c)
;       PU_LOAD_B(u0, xa0, xb0, id_c, s_c, t_c)
;     }
;     { const int tl_ = (s_n < 8) ? t_n : t_c; PU_LOAD_A(id_n, tl_) }
.LBB0_532:
	s_or_b64 exec, exec, s[2:3]
	v_mov_b32_e32 v0, v197
	s_barrier
	s_cmp_gt_i32 s18, 7
	v_readfirstlane_b32 s2, v0
	s_cbranch_scc1 .LBB0_542
	s_ashr_i32 s2, s2, 6
	s_add_u32 s4, s60, 0x1480000
	s_addc_u32 s5, s61, 0
	s_add_u32 s28, s60, 0xc7a0000
	s_addc_u32 s29, s61, 0
	s_add_u32 s30, s60, 0xd7a0000
	s_addc_u32 s31, s61, 0
	s_lshl_b32 s3, s91, 2
	s_add_i32 s6, s3, s2
	s_lshl_b32 s36, s90, 2
	s_add_i32 s2, s36, s6
	s_cmpk_gt_i32 s2, 0x3fff
	s_cselect_b32 s8, s6, s2
	s_cselect_b32 s2, s33, 0
	s_add_i32 s3, s8, s36
	s_add_i32 s10, s2, s18
	s_cmpk_gt_i32 s3, 0x3fff
	s_cselect_b32 s2, s33, 0
	s_cselect_b32 s11, s6, s3
	s_ashr_i32 s7, s6, 31
	s_add_i32 s17, s2, s10
	s_lshl_b64 s[2:3], s[6:7], 9
	v_lshlrev_b32_e32 v1, 1, v0
	s_add_u32 s2, s20, s2
	v_and_b32_e32 v152, 0x70, v1
	s_addc_u32 s3, s21, s3
	s_waitcnt vmcnt(17)
	v_lshlrev_b32_e32 v76, 2, v152
	global_load_dwordx4 v[4:7], v76, s[2:3]
	global_load_dwordx4 v[8:11], v76, s[2:3] offset:16
	global_load_dwordx4 v[12:15], v76, s[2:3] offset:32
	global_load_dwordx4 v[16:19], v76, s[2:3] offset:48
	s_lshl_b64 s[2:3], s[6:7], 10
	s_add_u32 s2, s28, s2
	s_addc_u32 s3, s29, s3
	s_lshl_b32 s9, s18, 7
	s_ashr_i32 s16, s9, 31
	s_add_u32 s2, s2, s9
	s_addc_u32 s3, s3, s16
	s_ashr_i32 s19, s18, 31
	s_lshl_b64 s[22:23], s[6:7], 5
	s_add_u32 s7, s30, s22
	s_addc_u32 s9, s31, s23
	s_lshl_b64 s[22:23], s[18:19], 2
	s_add_u32 s22, s7, s22
	v_and_b32_e32 v78, 7, v0
	s_addc_u32 s23, s9, s23
	v_lshlrev_b32_e32 v154, 4, v78
	s_cmp_lt_i32 s10, 8
	v_mov_b32_e32 v155, 0
	global_load_dwordx4 v[0:3], v154, s[2:3]
	global_load_dword v158, v155, s[22:23]
	s_cselect_b32 s2, s8, s6
	s_ashr_i32 s3, s2, 31
	s_lshl_b64 s[2:3], s[2:3], 9
	v_lshl_or_b32 v20, s18, 21, v154
	s_add_u32 s2, s20, s2
	s_addc_u32 s3, s21, s3
	global_load_dwordx4 v[68:71], v76, s[2:3] offset:48
	global_load_dwordx4 v[72:75], v76, s[2:3] offset:32
	s_mov_b32 s16, s6
	s_mov_b32 s22, s18
	s_waitcnt vmcnt(7)
	v_lshl_add_u32 v79, v4, 7, v20
	s_waitcnt vmcnt(6)
	v_lshl_add_u32 v9, v9, 7, v20
	v_lshl_add_u32 v8, v8, 7, v20
	v_lshl_add_u32 v11, v11, 7, v20
	v_lshl_add_u32 v10, v10, 7, v20
	v_lshl_add_u32 v77, v5, 7, v20
	v_lshl_add_u32 v80, v7, 7, v20
	v_lshl_add_u32 v81, v6, 7, v20
	s_waitcnt vmcnt(5)
	v_lshl_add_u32 v82, v13, 7, v20
	v_lshl_add_u32 v83, v12, 7, v20
	v_lshl_add_u32 v84, v15, 7, v20
	v_lshl_add_u32 v85, v14, 7, v20
	s_waitcnt vmcnt(4)
	v_lshl_add_u32 v86, v17, 7, v20
	v_lshl_add_u32 v87, v16, 7, v20
	v_lshl_add_u32 v88, v19, 7, v20
	v_lshl_add_u32 v89, v18, 7, v20
	global_load_dwordx4 v[64:67], v79, s[4:5]
	global_load_dwordx4 v[60:63], v77, s[4:5]
	global_load_dwordx4 v[56:59], v81, s[4:5]
	global_load_dwordx4 v[52:55], v80, s[4:5]
	global_load_dwordx4 v[48:51], v8, s[4:5]
	global_load_dwordx4 v[44:47], v9, s[4:5]
	global_load_dwordx4 v[40:43], v10, s[4:5]
	global_load_dwordx4 v[36:39], v11, s[4:5]
	global_load_dwordx4 v[32:35], v83, s[4:5]
	global_load_dwordx4 v[28:31], v82, s[4:5]
	global_load_dwordx4 v[24:27], v85, s[4:5]
	global_load_dwordx4 v[20:23], v84, s[4:5]
	global_load_dwordx4 v[16:19], v87, s[4:5]
	global_load_dwordx4 v[12:15], v86, s[4:5]
	global_load_dwordx4 v[4:7], v89, s[4:5]
	global_load_dwordx4 v[8:11], v88, s[4:5]
	global_load_dwordx4 v[92:95], v76, s[2:3] offset:16
	global_load_dwordx4 v[108:111], v76, s[2:3]
	v_mov_b32_e32 v77, v155
	v_lshl_add_u64 v[156:157], s[20:21], 0, v[76:77]
	v_cmp_eq_u32_e64 s[2:3], 0, v78
	s_waitcnt vmcnt(0)
	s_nop 0
	s_branch .LBB0_536

.LBB0_536:
	s_cmp_lt_i32 s10, 8
	s_cselect_b32 s26, s8, s16
	s_cselect_b32 s24, s10, s22
	s_ashr_i32 s27, s26, 31
	s_lshl_b64 s[38:39], s[26:27], 10
	s_add_u32 s9, s28, s38
	s_mov_b32 s7, s17
	s_mov_b32 s19, s11
	s_addc_u32 s11, s29, s39
	s_lshl_b32 s17, s24, 7
	s_ashr_i32 s23, s17, 31
	s_add_u32 s38, s9, s17
	s_addc_u32 s39, s11, s23
	s_ashr_i32 s25, s24, 31
	s_lshl_b64 s[26:27], s[26:27], 5
	s_add_u32 s9, s30, s26
	s_waitcnt vmcnt(6)
	v_lshl_or_b32 v76, s24, 21, v154
	s_addc_u32 s11, s31, s27
	s_lshl_b64 s[24:25], s[24:25], 2
	s_add_u32 s26, s9, s24
	s_addc_u32 s27, s11, s25
	s_cmp_lt_i32 s7, 8
	s_waitcnt vmcnt(2)
	v_lshl_add_u32 v77, v108, 7, v76
	s_cselect_b64 s[24:25], -1, 0
	v_lshl_add_u32 v78, v109, 7, v76
	global_load_dwordx4 v[148:151], v77, s[4:5]
	global_load_dwordx4 v[144:147], v78, s[4:5]
	v_lshl_add_u32 v77, v110, 7, v76
	v_lshl_add_u64 v[104:105], s[38:39], 0, v[154:155]
	s_and_b64 s[38:39], s[24:25], exec
	v_lshl_add_u32 v78, v111, 7, v76
	global_load_dwordx4 v[140:143], v77, s[4:5]
	global_load_dwordx4 v[136:139], v78, s[4:5]
	v_lshl_add_u32 v77, v92, 7, v76
	s_cselect_b32 s38, s19, s16
	v_lshl_add_u32 v78, v93, 7, v76
	global_load_dwordx4 v[132:135], v77, s[4:5]
	global_load_dwordx4 v[128:131], v78, s[4:5]
	v_lshl_add_u32 v77, v94, 7, v76
	v_lshl_add_u32 v72, v72, 7, v76
	s_ashr_i32 s39, s38, 31
	v_lshl_add_u32 v78, v95, 7, v76
	global_load_dwordx4 v[124:127], v77, s[4:5]
	global_load_dwordx4 v[120:123], v78, s[4:5]
	v_lshl_add_u32 v73, v73, 7, v76
	global_load_dwordx4 v[116:119], v72, s[4:5]
	global_load_dwordx4 v[112:115], v73, s[4:5]
	v_lshl_add_u32 v72, v74, 7, v76
	v_lshl_add_u32 v68, v68, 7, v76
	v_lshl_add_u32 v69, v69, 7, v76
	s_lshl_b64 s[38:39], s[38:39], 9
	v_lshl_add_u32 v73, v75, 7, v76
	global_load_dwordx4 v[100:103], v72, s[4:5]
	global_load_dwordx4 v[96:99], v73, s[4:5]
	global_load_dwordx4 v[88:91], v68, s[4:5]
	global_load_dwordx4 v[84:87], v69, s[4:5]
	v_lshl_add_u32 v68, v70, 7, v76
	v_lshl_add_u32 v69, v71, 7, v76
	v_lshl_add_u64 v[108:109], v[156:157], 0, s[38:39]
	global_load_dwordx4 v[80:83], v68, s[4:5]
	global_load_dwordx4 v[76:79], v69, s[4:5]
	global_load_dword v160, v155, s[26:27]
	s_nop 0
	global_load_dwordx4 v[68:71], v[108:109], off offset:48
	global_load_dwordx4 v[72:75], v[108:109], off offset:32
	global_load_dwordx4 v[92:95], v[108:109], off offset:16
	s_nop 0
	global_load_dwordx4 v[104:107], v[104:105], off
	s_nop 0
	global_load_dwordx4 v[108:111], v[108:109], off
	v_mov_b32_e32 v153, 0
	v_dot4c_i32_i8_e32 v153, v64, v0
	v_mov_b32_e32 v64, 0
	v_dot4c_i32_i8_e32 v64, v60, v0
	v_dot4c_i32_i8_e32 v64, v61, v1
	v_dot4c_i32_i8_e32 v64, v62, v2
	v_dot4c_i32_i8_e32 v64, v63, v3
	v_dot4c_i32_i8_e32 v153, v65, v1
	v_dot4c_i32_i8_e32 v153, v66, v2
	v_dot4c_i32_i8_e32 v153, v67, v3
	v_add_u32_dpp v60, v64, v64 quad_perm:[1,0,3,2] row_mask:0xf bank_mask:0xf bound_ctrl:1
	v_mov_b32_e32 v64, 0
	v_dot4c_i32_i8_e32 v64, v56, v0
	v_mov_b32_e32 v56, 0
	v_dot4c_i32_i8_e32 v56, v52, v0
	v_dot4c_i32_i8_e32 v56, v53, v1
	v_dot4c_i32_i8_e32 v56, v54, v2
	v_dot4c_i32_i8_e32 v56, v55, v3
	v_dot4c_i32_i8_e32 v64, v57, v1
	v_dot4c_i32_i8_e32 v64, v58, v2
	v_dot4c_i32_i8_e32 v64, v59, v3
	v_add_u32_dpp v52, v56, v56 quad_perm:[1,0,3,2] row_mask:0xf bank_mask:0xf bound_ctrl:1
	v_mov_b32_e32 v56, 0
	v_dot4c_i32_i8_e32 v56, v48, v0
	v_mov_b32_e32 v48, 0
	v_dot4c_i32_i8_e32 v48, v44, v0
	v_dot4c_i32_i8_e32 v48, v45, v1
	v_dot4c_i32_i8_e32 v48, v46, v2
	v_dot4c_i32_i8_e32 v48, v47, v3
	v_dot4c_i32_i8_e32 v56, v49, v1
	v_dot4c_i32_i8_e32 v56, v50, v2
	v_dot4c_i32_i8_e32 v56, v51, v3
	v_add_u32_dpp v44, v48, v48 quad_perm:[1,0,3,2] row_mask:0xf bank_mask:0xf bound_ctrl:1
	v_mov_b32_e32 v48, 0
	v_dot4c_i32_i8_e32 v48, v40, v0
	v_mov_b32_e32 v40, 0
	v_dot4c_i32_i8_e32 v40, v36, v0
	v_dot4c_i32_i8_e32 v40, v37, v1
	v_dot4c_i32_i8_e32 v40, v38, v2
	v_dot4c_i32_i8_e32 v40, v39, v3
	v_dot4c_i32_i8_e32 v48, v41, v1
	v_dot4c_i32_i8_e32 v48, v42, v2
	v_dot4c_i32_i8_e32 v48, v43, v3
	v_add_u32_dpp v36, v40, v40 quad_perm:[1,0,3,2] row_mask:0xf bank_mask:0xf bound_ctrl:1
	v_mov_b32_e32 v40, 0
	v_dot4c_i32_i8_e32 v40, v32, v0
	v_mov_b32_e32 v32, 0
	v_dot4c_i32_i8_e32 v32, v28, v0
	v_dot4c_i32_i8_e32 v32, v29, v1
	v_dot4c_i32_i8_e32 v32, v30, v2
	v_dot4c_i32_i8_e32 v32, v31, v3
	v_dot4c_i32_i8_e32 v40, v33, v1
	v_dot4c_i32_i8_e32 v40, v34, v2
	v_dot4c_i32_i8_e32 v40, v35, v3
	v_add_u32_dpp v28, v32, v32 quad_perm:[1,0,3,2] row_mask:0xf bank_mask:0xf bound_ctrl:1
	v_mov_b32_e32 v32, 0
	v_dot4c_i32_i8_e32 v32, v24, v0
	v_mov_b32_e32 v24, 0
	v_dot4c_i32_i8_e32 v24, v20, v0
	v_dot4c_i32_i8_e32 v24, v21, v1
	v_dot4c_i32_i8_e32 v24, v22, v2
	v_dot4c_i32_i8_e32 v24, v23, v3
	v_dot4c_i32_i8_e32 v32, v25, v1
	v_dot4c_i32_i8_e32 v32, v26, v2
	v_dot4c_i32_i8_e32 v32, v27, v3
	v_add_u32_dpp v20, v24, v24 quad_perm:[1,0,3,2] row_mask:0xf bank_mask:0xf bound_ctrl:1
	v_mov_b32_e32 v24, 0
	v_dot4c_i32_i8_e32 v24, v16, v0
	v_mov_b32_e32 v16, 0
	v_dot4c_i32_i8_e32 v16, v12, v0
	v_dot4c_i32_i8_e32 v16, v13, v1
	v_dot4c_i32_i8_e32 v16, v14, v2
	v_dot4c_i32_i8_e32 v16, v15, v3
	v_dot4c_i32_i8_e32 v24, v17, v1
	v_dot4c_i32_i8_e32 v24, v18, v2
	v_dot4c_i32_i8_e32 v24, v19, v3
	v_add_u32_dpp v12, v16, v16 quad_perm:[1,0,3,2] row_mask:0xf bank_mask:0xf bound_ctrl:1
	v_mov_b32_e32 v16, 0
	v_dot4c_i32_i8_e32 v16, v4, v0
	v_mov_b32_e32 v4, 0
	v_dot4c_i32_i8_e32 v4, v8, v0
	v_dot4c_i32_i8_e32 v16, v5, v1
	v_dot4c_i32_i8_e32 v4, v9, v1
	v_dot4c_i32_i8_e32 v16, v6, v2
	v_dot4c_i32_i8_e32 v4, v10, v2
	v_dot4c_i32_i8_e32 v16, v7, v3
	v_dot4c_i32_i8_e32 v4, v11, v3
	v_add_u32_dpp v61, v153, v153 quad_perm:[1,0,3,2] row_mask:0xf bank_mask:0xf bound_ctrl:1
	v_add_u32_dpp v53, v64, v64 quad_perm:[1,0,3,2] row_mask:0xf bank_mask:0xf bound_ctrl:1
	v_add_u32_dpp v45, v56, v56 quad_perm:[1,0,3,2] row_mask:0xf bank_mask:0xf bound_ctrl:1
	v_add_u32_dpp v37, v48, v48 quad_perm:[1,0,3,2] row_mask:0xf bank_mask:0xf bound_ctrl:1
	v_add_u32_dpp v29, v40, v40 quad_perm:[1,0,3,2] row_mask:0xf bank_mask:0xf bound_ctrl:1
	v_add_u32_dpp v21, v32, v32 quad_perm:[1,0,3,2] row_mask:0xf bank_mask:0xf bound_ctrl:1
	v_add_u32_dpp v13, v24, v24 quad_perm:[1,0,3,2] row_mask:0xf bank_mask:0xf bound_ctrl:1
	v_add_u32_dpp v0, v4, v4 quad_perm:[1,0,3,2] row_mask:0xf bank_mask:0xf bound_ctrl:1
	v_add_u32_dpp v1, v16, v16 quad_perm:[1,0,3,2] row_mask:0xf bank_mask:0xf bound_ctrl:1
	v_add_u32_dpp v60, v60, v60 quad_perm:[2,3,0,1] row_mask:0xf bank_mask:0xf bound_ctrl:1
	v_add_u32_dpp v61, v61, v61 quad_perm:[2,3,0,1] row_mask:0xf bank_mask:0xf bound_ctrl:1
	v_add_u32_dpp v52, v52, v52 quad_perm:[2,3,0,1] row_mask:0xf bank_mask:0xf bound_ctrl:1
	v_add_u32_dpp v53, v53, v53 quad_perm:[2,3,0,1] row_mask:0xf bank_mask:0xf bound_ctrl:1
	v_add_u32_dpp v44, v44, v44 quad_perm:[2,3,0,1] row_mask:0xf bank_mask:0xf bound_ctrl:1
	v_add_u32_dpp v46, v45, v45 quad_perm:[2,3,0,1] row_mask:0xf bank_mask:0xf bound_ctrl:1
	v_add_u32_dpp v36, v36, v36 quad_perm:[2,3,0,1] row_mask:0xf bank_mask:0xf bound_ctrl:1
	v_add_u32_dpp v37, v37, v37 quad_perm:[2,3,0,1] row_mask:0xf bank_mask:0xf bound_ctrl:1
	v_add_u32_dpp v28, v28, v28 quad_perm:[2,3,0,1] row_mask:0xf bank_mask:0xf bound_ctrl:1
	v_add_u32_dpp v29, v29, v29 quad_perm:[2,3,0,1] row_mask:0xf bank_mask:0xf bound_ctrl:1
	v_add_u32_dpp v20, v20, v20 quad_perm:[2,3,0,1] row_mask:0xf bank_mask:0xf bound_ctrl:1
	v_add_u32_dpp v21, v21, v21 quad_perm:[2,3,0,1] row_mask:0xf bank_mask:0xf bound_ctrl:1
	v_add_u32_dpp v12, v12, v12 quad_perm:[2,3,0,1] row_mask:0xf bank_mask:0xf bound_ctrl:1
	v_add_u32_dpp v13, v13, v13 quad_perm:[2,3,0,1] row_mask:0xf bank_mask:0xf bound_ctrl:1
	v_add_u32_dpp v0, v0, v0 quad_perm:[2,3,0,1] row_mask:0xf bank_mask:0xf bound_ctrl:1
	v_add_u32_dpp v1, v1, v1 quad_perm:[2,3,0,1] row_mask:0xf bank_mask:0xf bound_ctrl:1
	v_mov_b32_dpp v62, v61 row_half_mirror row_mask:0xf bank_mask:0xf bound_ctrl:1
	v_mov_b32_dpp v63, v60 row_half_mirror row_mask:0xf bank_mask:0xf bound_ctrl:1
	v_mov_b32_dpp v54, v53 row_half_mirror row_mask:0xf bank_mask:0xf bound_ctrl:1
	v_mov_b32_dpp v55, v52 row_half_mirror row_mask:0xf bank_mask:0xf bound_ctrl:1
	v_mov_b32_dpp v47, v46 row_half_mirror row_mask:0xf bank_mask:0xf bound_ctrl:1
	v_mov_b32_dpp v45, v44 row_half_mirror row_mask:0xf bank_mask:0xf bound_ctrl:1
	v_mov_b32_dpp v38, v37 row_half_mirror row_mask:0xf bank_mask:0xf bound_ctrl:1
	v_mov_b32_dpp v39, v36 row_half_mirror row_mask:0xf bank_mask:0xf bound_ctrl:1
	v_mov_b32_dpp v30, v29 row_half_mirror row_mask:0xf bank_mask:0xf bound_ctrl:1
	v_mov_b32_dpp v31, v28 row_half_mirror row_mask:0xf bank_mask:0xf bound_ctrl:1
	v_mov_b32_dpp v22, v21 row_half_mirror row_mask:0xf bank_mask:0xf bound_ctrl:1
	v_mov_b32_dpp v23, v20 row_half_mirror row_mask:0xf bank_mask:0xf bound_ctrl:1
	v_mov_b32_dpp v14, v13 row_half_mirror row_mask:0xf bank_mask:0xf bound_ctrl:1
	v_mov_b32_dpp v15, v12 row_half_mirror row_mask:0xf bank_mask:0xf bound_ctrl:1
	v_mov_b32_dpp v2, v1 row_half_mirror row_mask:0xf bank_mask:0xf bound_ctrl:1
	v_mov_b32_dpp v3, v0 row_half_mirror row_mask:0xf bank_mask:0xf bound_ctrl:1
	s_and_saveexec_b64 s[26:27], s[2:3]
	s_cbranch_execz .LBB0_538
	v_add_u32_e32 v10, v1, v2
	v_add_u32_e32 v11, v0, v3
	v_add_u32_e32 v2, v53, v54
	v_add_u32_e32 v3, v52, v55
	v_add_u32_e32 v0, v61, v62
	v_add_u32_e32 v1, v60, v63
	v_add_u32_e32 v6, v37, v38
	v_add_u32_e32 v7, v36, v39
	v_add_u32_e32 v4, v46, v47
	v_cvt_f32_i32_e32 v1, v1
	v_cvt_f32_i32_e32 v0, v0
	v_cvt_f32_i32_e32 v3, v3
	v_cvt_f32_i32_e32 v2, v2
	v_add_u32_e32 v5, v44, v45
	v_cvt_f32_i32_e32 v5, v5
	v_cvt_f32_i32_e32 v4, v4
	v_cvt_f32_i32_e32 v7, v7
	v_cvt_f32_i32_e32 v6, v6
	v_add_u32_e32 v13, v13, v14
	v_add_u32_e32 v12, v12, v15
	v_add_u32_e32 v8, v21, v22
	v_add_u32_e32 v9, v20, v23
	v_add_u32_e32 v14, v29, v30
	v_add_u32_e32 v15, v28, v31
	v_pk_mul_f32 v[0:1], v[158:159], v[0:1] op_sel_hi:[0,1]
	v_pk_mul_f32 v[2:3], v[158:159], v[2:3] op_sel_hi:[0,1]
	v_cvt_pk_f16_f32 v0, v0, v1
	v_cvt_pk_f16_f32 v1, v2, v3
	v_pk_mul_f32 v[2:3], v[158:159], v[4:5] op_sel_hi:[0,1]
	v_pk_mul_f32 v[4:5], v[158:159], v[6:7] op_sel_hi:[0,1]
	v_cvt_f32_i32_e32 v7, v15
	v_cvt_f32_i32_e32 v6, v14
	v_cvt_f32_i32_e32 v9, v9
	v_cvt_f32_i32_e32 v8, v8
	v_cvt_pk_f16_f32 v2, v2, v3
	v_cvt_pk_f16_f32 v3, v4, v5
	v_pk_mul_f32 v[4:5], v[158:159], v[6:7] op_sel_hi:[0,1]
	v_pk_mul_f32 v[6:7], v[158:159], v[8:9] op_sel_hi:[0,1]
	v_cvt_f32_i32_e32 v9, v12
	v_cvt_f32_i32_e32 v8, v13
	v_cvt_f32_i32_e32 v11, v11
	v_cvt_f32_i32_e32 v10, v10
	s_ashr_i32 s23, s22, 31
	s_ashr_i32 s17, s16, 31
	s_lshl_b64 s[22:23], s[22:23], 22
	s_add_u32 s9, s14, s22
	s_addc_u32 s11, s15, s23
	s_lshl_b64 s[16:17], s[16:17], 8
	v_cvt_pk_f16_f32 v4, v4, v5
	v_cvt_pk_f16_f32 v5, v6, v7
	v_pk_mul_f32 v[6:7], v[158:159], v[8:9] op_sel_hi:[0,1]
	v_pk_mul_f32 v[8:9], v[158:159], v[10:11] op_sel_hi:[0,1]
	s_add_u32 s16, s9, s16
	v_cvt_pk_f16_f32 v6, v6, v7
	v_cvt_pk_f16_f32 v7, v8, v9
	s_addc_u32 s17, s11, s17
	v_lshlrev_b32_e32 v8, 1, v152
	global_store_dwordx4 v8, v[0:3], s[16:17]
	global_store_dwordx4 v8, v[4:7], s[16:17] offset:16
.LBB0_538:
	s_or_b64 exec, exec, s[26:27]
	s_cmp_gt_i32 s10, 7
	s_cbranch_scc1 .LBB0_541
	s_add_i32 s9, s19, s36
	s_cmpk_gt_i32 s9, 0x3fff
	s_cselect_b32 s23, s6, s9
	s_cselect_b32 s9, s33, 0
	s_add_i32 s22, s9, s7
	s_and_b64 s[16:17], s[24:25], exec
	s_cselect_b32 s24, s19, s8
	s_cselect_b32 s16, s7, s10
	s_ashr_i32 s25, s24, 31
	s_lshl_b64 s[26:27], s[24:25], 10
	s_add_u32 s9, s28, s26
	s_addc_u32 s11, s29, s27
	s_lshl_b32 s17, s16, 7
	s_ashr_i32 s27, s17, 31
	s_add_u32 s26, s9, s17
	v_lshl_or_b32 v0, s16, 21, v154
	s_addc_u32 s27, s11, s27
	s_ashr_i32 s17, s16, 31
	s_lshl_b64 s[24:25], s[24:25], 5
	s_waitcnt vmcnt(2)
	v_lshl_add_u32 v1, v108, 7, v0
	s_add_u32 s9, s30, s24
	v_lshl_add_u32 v2, v109, 7, v0
	global_load_dwordx4 v[64:67], v1, s[4:5]
	global_load_dwordx4 v[60:63], v2, s[4:5]
	v_lshl_add_u32 v1, v110, 7, v0
	s_addc_u32 s11, s31, s25
	s_lshl_b64 s[16:17], s[16:17], 2
	v_lshl_add_u32 v2, v111, 7, v0
	global_load_dwordx4 v[56:59], v1, s[4:5]
	global_load_dwordx4 v[52:55], v2, s[4:5]
	v_lshl_add_u32 v1, v92, 7, v0
	s_add_u32 s16, s9, s16
	v_lshl_add_u32 v2, v93, 7, v0
	global_load_dwordx4 v[48:51], v1, s[4:5]
	global_load_dwordx4 v[44:47], v2, s[4:5]
	v_lshl_add_u32 v1, v94, 7, v0
	s_addc_u32 s17, s11, s17
	v_lshl_add_u32 v2, v95, 7, v0
	global_load_dwordx4 v[40:43], v1, s[4:5]
	global_load_dwordx4 v[36:39], v2, s[4:5]
	v_lshl_add_u32 v1, v72, 7, v0
	s_cmp_lt_i32 s22, 8
	v_lshl_add_u32 v2, v73, 7, v0
	global_load_dwordx4 v[32:35], v1, s[4:5]
	global_load_dwordx4 v[28:31], v2, s[4:5]
	v_lshl_add_u32 v1, v74, 7, v0
	s_cselect_b32 s24, s23, s8
	v_lshl_add_u32 v2, v75, 7, v0
	global_load_dwordx4 v[24:27], v1, s[4:5]
	global_load_dwordx4 v[20:23], v2, s[4:5]
	v_lshl_add_u32 v1, v68, 7, v0
	s_ashr_i32 s25, s24, 31
	v_lshl_add_u32 v2, v69, 7, v0
	global_load_dwordx4 v[16:19], v1, s[4:5]
	global_load_dwordx4 v[12:15], v2, s[4:5]
	v_lshl_add_u32 v1, v70, 7, v0
	v_lshl_add_u32 v0, v71, 7, v0
	s_lshl_b64 s[24:25], s[24:25], 9
	global_load_dwordx4 v[4:7], v1, s[4:5]
	global_load_dwordx4 v[8:11], v0, s[4:5]
	v_lshl_add_u64 v[0:1], s[26:27], 0, v[154:155]
	v_lshl_add_u64 v[108:109], v[156:157], 0, s[24:25]
	global_load_dword v158, v155, s[16:17]
	global_load_dwordx4 v[68:71], v[108:109], off offset:48
	global_load_dwordx4 v[72:75], v[108:109], off offset:32
	global_load_dwordx4 v[92:95], v[108:109], off offset:16
	s_nop 0
	global_load_dwordx4 v[0:3], v[0:1], off
	s_nop 0
	global_load_dwordx4 v[108:111], v[108:109], off
	v_mov_b32_e32 v153, 0
	v_dot4c_i32_i8_e32 v153, v148, v104
	v_mov_b32_e32 v148, 0
	v_dot4c_i32_i8_e32 v148, v144, v104
	v_dot4c_i32_i8_e32 v148, v145, v105
	v_dot4c_i32_i8_e32 v148, v146, v106
	v_dot4c_i32_i8_e32 v148, v147, v107
	v_dot4c_i32_i8_e32 v153, v149, v105
	v_dot4c_i32_i8_e32 v153, v150, v106
	v_dot4c_i32_i8_e32 v153, v151, v107
	v_add_u32_dpp v144, v148, v148 quad_perm:[1,0,3,2] row_mask:0xf bank_mask:0xf bound_ctrl:1
	v_mov_b32_e32 v148, 0
	v_dot4c_i32_i8_e32 v148, v140, v104
	v_mov_b32_e32 v140, 0
	v_dot4c_i32_i8_e32 v140, v136, v104
	v_dot4c_i32_i8_e32 v140, v137, v105
	v_dot4c_i32_i8_e32 v140, v138, v106
	v_dot4c_i32_i8_e32 v140, v139, v107
	v_dot4c_i32_i8_e32 v148, v141, v105
	v_dot4c_i32_i8_e32 v148, v142, v106
	v_dot4c_i32_i8_e32 v148, v143, v107
	v_add_u32_dpp v136, v140, v140 quad_perm:[1,0,3,2] row_mask:0xf bank_mask:0xf bound_ctrl:1
	v_mov_b32_e32 v140, 0
	v_dot4c_i32_i8_e32 v140, v132, v104
	v_mov_b32_e32 v132, 0
	v_dot4c_i32_i8_e32 v132, v128, v104
	v_dot4c_i32_i8_e32 v132, v129, v105
	v_dot4c_i32_i8_e32 v132, v130, v106
	v_dot4c_i32_i8_e32 v132, v131, v107
	v_dot4c_i32_i8_e32 v140, v133, v105
	v_dot4c_i32_i8_e32 v140, v134, v106
	v_dot4c_i32_i8_e32 v140, v135, v107
	v_add_u32_dpp v128, v132, v132 quad_perm:[1,0,3,2] row_mask:0xf bank_mask:0xf bound_ctrl:1
	v_mov_b32_e32 v132, 0
	v_dot4c_i32_i8_e32 v132, v124, v104
	v_mov_b32_e32 v124, 0
	v_dot4c_i32_i8_e32 v124, v120, v104
	v_dot4c_i32_i8_e32 v124, v121, v105
	v_dot4c_i32_i8_e32 v124, v122, v106
	v_dot4c_i32_i8_e32 v124, v123, v107
	v_dot4c_i32_i8_e32 v132, v125, v105
	v_dot4c_i32_i8_e32 v132, v126, v106
	v_dot4c_i32_i8_e32 v132, v127, v107
	v_add_u32_dpp v120, v124, v124 quad_perm:[1,0,3,2] row_mask:0xf bank_mask:0xf bound_ctrl:1
	v_mov_b32_e32 v124, 0
	v_dot4c_i32_i8_e32 v124, v116, v104
	v_mov_b32_e32 v116, 0
	v_dot4c_i32_i8_e32 v116, v112, v104
	v_dot4c_i32_i8_e32 v116, v113, v105
	v_dot4c_i32_i8_e32 v116, v114, v106
	v_dot4c_i32_i8_e32 v116, v115, v107
	v_dot4c_i32_i8_e32 v124, v117, v105
	v_dot4c_i32_i8_e32 v124, v118, v106
	v_dot4c_i32_i8_e32 v124, v119, v107
	v_add_u32_dpp v112, v116, v116 quad_perm:[1,0,3,2] row_mask:0xf bank_mask:0xf bound_ctrl:1
	v_mov_b32_e32 v116, 0
	v_dot4c_i32_i8_e32 v116, v100, v104
	v_mov_b32_e32 v100, 0
	v_dot4c_i32_i8_e32 v100, v96, v104
	v_dot4c_i32_i8_e32 v100, v97, v105
	v_dot4c_i32_i8_e32 v100, v98, v106
	v_dot4c_i32_i8_e32 v100, v99, v107
	v_dot4c_i32_i8_e32 v116, v101, v105
	v_dot4c_i32_i8_e32 v116, v102, v106
	v_dot4c_i32_i8_e32 v116, v103, v107
	v_add_u32_dpp v96, v100, v100 quad_perm:[1,0,3,2] row_mask:0xf bank_mask:0xf bound_ctrl:1
	v_mov_b32_e32 v100, 0
	v_dot4c_i32_i8_e32 v100, v88, v104
	v_mov_b32_e32 v88, 0
	v_dot4c_i32_i8_e32 v88, v84, v104
	v_dot4c_i32_i8_e32 v88, v85, v105
	v_dot4c_i32_i8_e32 v88, v86, v106
	v_dot4c_i32_i8_e32 v88, v87, v107
	v_dot4c_i32_i8_e32 v100, v89, v105
	v_dot4c_i32_i8_e32 v100, v90, v106
	v_dot4c_i32_i8_e32 v100, v91, v107
	v_add_u32_dpp v84, v88, v88 quad_perm:[1,0,3,2] row_mask:0xf bank_mask:0xf bound_ctrl:1
	v_mov_b32_e32 v88, 0
	v_dot4c_i32_i8_e32 v88, v80, v104
	v_mov_b32_e32 v80, 0
	v_dot4c_i32_i8_e32 v80, v76, v104
	v_dot4c_i32_i8_e32 v88, v81, v105
	v_dot4c_i32_i8_e32 v80, v77, v105
	v_dot4c_i32_i8_e32 v88, v82, v106
	v_dot4c_i32_i8_e32 v80, v78, v106
	v_dot4c_i32_i8_e32 v88, v83, v107
	v_dot4c_i32_i8_e32 v80, v79, v107
	v_add_u32_dpp v145, v153, v153 quad_perm:[1,0,3,2] row_mask:0xf bank_mask:0xf bound_ctrl:1
	v_add_u32_dpp v137, v148, v148 quad_perm:[1,0,3,2] row_mask:0xf bank_mask:0xf bound_ctrl:1
	v_add_u32_dpp v129, v140, v140 quad_perm:[1,0,3,2] row_mask:0xf bank_mask:0xf bound_ctrl:1
	v_add_u32_dpp v121, v132, v132 quad_perm:[1,0,3,2] row_mask:0xf bank_mask:0xf bound_ctrl:1
	v_add_u32_dpp v113, v124, v124 quad_perm:[1,0,3,2] row_mask:0xf bank_mask:0xf bound_ctrl:1
	v_add_u32_dpp v97, v116, v116 quad_perm:[1,0,3,2] row_mask:0xf bank_mask:0xf bound_ctrl:1
	v_add_u32_dpp v85, v100, v100 quad_perm:[1,0,3,2] row_mask:0xf bank_mask:0xf bound_ctrl:1
	v_add_u32_dpp v76, v80, v80 quad_perm:[1,0,3,2] row_mask:0xf bank_mask:0xf bound_ctrl:1
	v_add_u32_dpp v77, v88, v88 quad_perm:[1,0,3,2] row_mask:0xf bank_mask:0xf bound_ctrl:1
	v_add_u32_dpp v144, v144, v144 quad_perm:[2,3,0,1] row_mask:0xf bank_mask:0xf bound_ctrl:1
	v_add_u32_dpp v145, v145, v145 quad_perm:[2,3,0,1] row_mask:0xf bank_mask:0xf bound_ctrl:1
	v_add_u32_dpp v136, v136, v136 quad_perm:[2,3,0,1] row_mask:0xf bank_mask:0xf bound_ctrl:1
	v_add_u32_dpp v137, v137, v137 quad_perm:[2,3,0,1] row_mask:0xf bank_mask:0xf bound_ctrl:1
	v_add_u32_dpp v128, v128, v128 quad_perm:[2,3,0,1] row_mask:0xf bank_mask:0xf bound_ctrl:1
	v_add_u32_dpp v130, v129, v129 quad_perm:[2,3,0,1] row_mask:0xf bank_mask:0xf bound_ctrl:1
	v_add_u32_dpp v120, v120, v120 quad_perm:[2,3,0,1] row_mask:0xf bank_mask:0xf bound_ctrl:1
	v_add_u32_dpp v121, v121, v121 quad_perm:[2,3,0,1] row_mask:0xf bank_mask:0xf bound_ctrl:1
	v_add_u32_dpp v112, v112, v112 quad_perm:[2,3,0,1] row_mask:0xf bank_mask:0xf bound_ctrl:1
	v_add_u32_dpp v113, v113, v113 quad_perm:[2,3,0,1] row_mask:0xf bank_mask:0xf bound_ctrl:1
	v_add_u32_dpp v96, v96, v96 quad_perm:[2,3,0,1] row_mask:0xf bank_mask:0xf bound_ctrl:1
	v_add_u32_dpp v97, v97, v97 quad_perm:[2,3,0,1] row_mask:0xf bank_mask:0xf bound_ctrl:1
	v_add_u32_dpp v84, v84, v84 quad_perm:[2,3,0,1] row_mask:0xf bank_mask:0xf bound_ctrl:1
	v_add_u32_dpp v85, v85, v85 quad_perm:[2,3,0,1] row_mask:0xf bank_mask:0xf bound_ctrl:1
	v_add_u32_dpp v76, v76, v76 quad_perm:[2,3,0,1] row_mask:0xf bank_mask:0xf bound_ctrl:1
	v_add_u32_dpp v77, v77, v77 quad_perm:[2,3,0,1] row_mask:0xf bank_mask:0xf bound_ctrl:1
	v_mov_b32_dpp v146, v145 row_half_mirror row_mask:0xf bank_mask:0xf bound_ctrl:1
	v_mov_b32_dpp v147, v144 row_half_mirror row_mask:0xf bank_mask:0xf bound_ctrl:1
	v_mov_b32_dpp v138, v137 row_half_mirror row_mask:0xf bank_mask:0xf bound_ctrl:1
	v_mov_b32_dpp v139, v136 row_half_mirror row_mask:0xf bank_mask:0xf bound_ctrl:1
	v_mov_b32_dpp v131, v130 row_half_mirror row_mask:0xf bank_mask:0xf bound_ctrl:1
	v_mov_b32_dpp v129, v128 row_half_mirror row_mask:0xf bank_mask:0xf bound_ctrl:1
	v_mov_b32_dpp v122, v121 row_half_mirror row_mask:0xf bank_mask:0xf bound_ctrl:1
	v_mov_b32_dpp v123, v120 row_half_mirror row_mask:0xf bank_mask:0xf bound_ctrl:1
	v_mov_b32_dpp v114, v113 row_half_mirror row_mask:0xf bank_mask:0xf bound_ctrl:1
	v_mov_b32_dpp v115, v112 row_half_mirror row_mask:0xf bank_mask:0xf bound_ctrl:1
	v_mov_b32_dpp v98, v97 row_half_mirror row_mask:0xf bank_mask:0xf bound_ctrl:1
	v_mov_b32_dpp v99, v96 row_half_mirror row_mask:0xf bank_mask:0xf bound_ctrl:1
	v_mov_b32_dpp v86, v85 row_half_mirror row_mask:0xf bank_mask:0xf bound_ctrl:1
	v_mov_b32_dpp v87, v84 row_half_mirror row_mask:0xf bank_mask:0xf bound_ctrl:1
	v_mov_b32_dpp v78, v77 row_half_mirror row_mask:0xf bank_mask:0xf bound_ctrl:1
	v_mov_b32_dpp v79, v76 row_half_mirror row_mask:0xf bank_mask:0xf bound_ctrl:1
	s_and_saveexec_b64 s[16:17], s[2:3]
	s_cbranch_execz .LBB0_534
	v_add_u32_e32 v88, v77, v78
	v_add_u32_e32 v89, v76, v79
	v_add_u32_e32 v78, v137, v138
	v_add_u32_e32 v79, v136, v139
	v_add_u32_e32 v76, v145, v146
	v_add_u32_e32 v77, v144, v147
	v_add_u32_e32 v82, v121, v122
	v_add_u32_e32 v83, v120, v123
	v_add_u32_e32 v80, v130, v131
	v_cvt_f32_i32_e32 v77, v77
	v_cvt_f32_i32_e32 v76, v76
	v_cvt_f32_i32_e32 v79, v79
	v_cvt_f32_i32_e32 v78, v78
	v_add_u32_e32 v81, v128, v129
	v_cvt_f32_i32_e32 v81, v81
	v_cvt_f32_i32_e32 v80, v80
	v_cvt_f32_i32_e32 v83, v83
	v_cvt_f32_i32_e32 v82, v82
	v_add_u32_e32 v86, v85, v86
	v_add_u32_e32 v87, v84, v87
	v_add_u32_e32 v84, v97, v98
	v_add_u32_e32 v85, v96, v99
	v_add_u32_e32 v90, v113, v114
	v_add_u32_e32 v91, v112, v115
	v_pk_mul_f32 v[76:77], v[160:161], v[76:77] op_sel_hi:[0,1]
	v_pk_mul_f32 v[78:79], v[160:161], v[78:79] op_sel_hi:[0,1]
	v_cvt_pk_f16_f32 v76, v76, v77
	v_cvt_pk_f16_f32 v77, v78, v79
	v_pk_mul_f32 v[78:79], v[160:161], v[80:81] op_sel_hi:[0,1]
	v_pk_mul_f32 v[80:81], v[160:161], v[82:83] op_sel_hi:[0,1]
	v_cvt_f32_i32_e32 v83, v91
	v_cvt_f32_i32_e32 v82, v90
	v_cvt_f32_i32_e32 v85, v85
	v_cvt_f32_i32_e32 v84, v84
	v_cvt_pk_f16_f32 v78, v78, v79
	v_cvt_pk_f16_f32 v79, v80, v81
	v_pk_mul_f32 v[80:81], v[160:161], v[82:83] op_sel_hi:[0,1]
	v_pk_mul_f32 v[82:83], v[160:161], v[84:85] op_sel_hi:[0,1]
	v_cvt_f32_i32_e32 v85, v87
	v_cvt_f32_i32_e32 v84, v86
	v_cvt_f32_i32_e32 v87, v89
	v_cvt_f32_i32_e32 v86, v88
	s_ashr_i32 s11, s10, 31
	s_ashr_i32 s9, s8, 31
	s_lshl_b64 s[10:11], s[10:11], 22
	s_add_u32 s10, s14, s10
	s_addc_u32 s11, s15, s11
	s_lshl_b64 s[8:9], s[8:9], 8
	v_cvt_pk_f16_f32 v80, v80, v81
	v_cvt_pk_f16_f32 v81, v82, v83
	v_pk_mul_f32 v[82:83], v[160:161], v[84:85] op_sel_hi:[0,1]
	v_pk_mul_f32 v[84:85], v[160:161], v[86:87] op_sel_hi:[0,1]
	s_add_u32 s8, s10, s8
	v_cvt_pk_f16_f32 v82, v82, v83
	v_cvt_pk_f16_f32 v83, v84, v85
	s_addc_u32 s9, s11, s9
	v_lshlrev_b32_e32 v84, 1, v152
	global_store_dwordx4 v84, v[76:79], s[8:9]
	global_store_dwordx4 v84, v[80:83], s[8:9] offset:16
	s_branch .LBB0_534

; __device__ __forceinline__ int opaque_tid() { int t = threadIdx.x; asm volatile("" : "+v"(t)); return t; }
; #define PV_LOAD_A(ID, tt) { _Pragma("unroll") for (int i = 0; i < 4; ++i) ID[i] = *(const int4*)(selE + (size_t)(tt) * 128 + sub * 16 + 4 * i); }
; __device__ void phase_pv(const Params& p, const XcdBarrier& xb) {
;   const int tid = opaque_tid(), lane = tid & 63;
;   const int w = __builtin_amdgcn_readfirstlane(tid >> 6);
;   const int sub = lane >> 3, c8 = lane & 7;
;   char* ws = p.ws;
;   const int* selE = (const int*)(ws + OFF_SELE);
;   const unsigned* coef = (const unsigned*)(ws + OFF_COEF);
;   const unsigned char* ev = (const unsigned char*)(ws + OFF_EV);
;   bf16_t* yb = (bf16_t*)(ws + OFF_PART);
;   const int wrank = __builtin_amdgcn_readfirstlane((int)xb.rank) * 4 + w;
;   const int nw = __builtin_amdgcn_readfirstlane((int)xb.nloc) * 4;
;   const int nx = __builtin_amdgcn_readfirstlane((int)xb.nx);
;   const int xi = __builtin_amdgcn_readfirstlane((int)xb.xi);
;   const int ci = ((((lane >> 5) & 1) << 2) | (((lane >> 4) & 1) << 1) | ((lane >> 3) & 1)) * 2;
;   u32x4 v0[16], v1[16];
;   u32x4 cf0[4], cf1[4];
;   float2 hold0, hold1;
;   int4 id_n[4], id_nn[4];
;   int s_c = xi, t_c = wrank;
;   int s_n = s_c, t_n = t_c + nw; if (t_n >= T) { t_n = wrank; s_n += nx; }
;   int s_nn = s_n, t_nn = t_n + nw; if (t_nn >= T) { t_nn = wrank; s_nn += nx; }
;     ...
;   if (s_c < 8) {
;     {
;       int4 id_c[4];
;       PV_LOAD_A(id_c, t_c)
;       PV_LOAD_B(v0, cf0, hold0, id_c, s_c, t_c)
;     }
;     { const int tl_ = (s_n < 8) ? t_n : t_c; PV_LOAD_A(id_n, tl_) }
.LBB0_619:
	s_or_b64 exec, exec, s[2:3]
	v_mov_b32_e32 v80, v197
	s_barrier
	s_cmp_gt_i32 s18, 7
	v_readfirstlane_b32 s2, v80
	s_cbranch_scc1 .LBB0_624
	s_ashr_i32 s2, s2, 6
	s_add_u32 s4, s60, 0x3480000
	s_addc_u32 s5, s61, 0
	s_lshl_b32 s3, s91, 2
	s_add_i32 s6, s3, s2
	s_lshl_b32 s19, s90, 2
	s_add_i32 s2, s19, s6
	s_cmpk_gt_i32 s2, 0x3fff
	s_cselect_b32 s8, s6, s2
	s_cselect_b32 s2, s33, 0
	s_add_i32 s3, s8, s19
	s_add_i32 s22, s2, s18
	s_cmpk_gt_i32 s3, 0x3fff
	s_cselect_b32 s2, s33, 0
	s_cselect_b32 s26, s6, s3
	s_ashr_i32 s7, s6, 31
	s_add_i32 s27, s2, s22
	s_lshl_b64 s[2:3], s[6:7], 9
	s_add_u32 s16, s20, s2
	v_lshlrev_b32_e32 v0, 3, v80
	s_addc_u32 s17, s21, s3
	v_and_b32_e32 v194, 0x1c0, v0
	global_load_dwordx4 v[4:7], v194, s[16:17]
	global_load_dwordx4 v[8:11], v194, s[16:17] offset:16
	global_load_dwordx4 v[16:19], v194, s[16:17] offset:32
	global_load_dwordx4 v[20:23], v194, s[16:17] offset:48
	s_add_u32 s2, s10, s2
	s_addc_u32 s3, s11, s3
	v_lshlrev_b32_e32 v0, 4, v80
	s_cmp_lt_i32 s22, 8
	v_and_b32_e32 v196, 0x70, v0
	global_load_dwordx4 v[0:3], v194, s[2:3] offset:48
	global_load_dwordx4 v[12:15], v194, s[2:3] offset:32
	global_load_dwordx4 v[36:39], v194, s[2:3] offset:16
	global_load_dwordx4 v[60:63], v194, s[2:3]
	s_cselect_b32 s2, s8, s6
	s_ashr_i32 s3, s2, 31
	s_lshl_b64 s[2:3], s[2:3], 9
	v_lshl_or_b32 v24, s18, 21, v196
	s_add_u32 s2, s20, s2
	s_addc_u32 s3, s21, s3
	global_load_dwordx4 v[100:103], v194, s[2:3] offset:48
	global_load_dwordx4 v[108:111], v194, s[2:3] offset:32
	v_mov_b32_e32 v195, 0
	v_lshl_add_u64 v[198:199], s[10:11], 0, v[194:195]
	v_lshl_add_u64 v[200:201], s[20:21], 0, v[194:195]
	s_mov_b32 s10, 0x3b800000
	s_movk_i32 s7, 0x7fff
	s_mov_b32 s11, 0xffff0000
	v_mov_b32_e32 v205, v195
	v_mov_b32_e32 v208, 1
	s_mov_b32 s23, s6
	s_waitcnt vmcnt(9)
	v_lshl_add_u32 v82, v4, 7, v24
	s_waitcnt vmcnt(8)
	v_lshl_add_u32 v9, v9, 7, v24
	v_lshl_add_u32 v8, v8, 7, v24
	v_lshl_add_u32 v11, v11, 7, v24
	v_lshl_add_u32 v10, v10, 7, v24
	v_lshl_add_u32 v81, v5, 7, v24
	v_lshl_add_u32 v83, v7, 7, v24
	v_lshl_add_u32 v84, v6, 7, v24
	s_waitcnt vmcnt(7)
	v_lshl_add_u32 v85, v17, 7, v24
	v_lshl_add_u32 v86, v16, 7, v24
	v_lshl_add_u32 v87, v19, 7, v24
	v_lshl_add_u32 v88, v18, 7, v24
	s_waitcnt vmcnt(6)
	v_lshl_add_u32 v89, v21, 7, v24
	v_lshl_add_u32 v90, v20, 7, v24
	v_lshl_add_u32 v91, v23, 7, v24
	v_lshl_add_u32 v92, v22, 7, v24
	global_load_dwordx4 v[76:79], v82, s[4:5]
	global_load_dwordx4 v[72:75], v81, s[4:5]
	global_load_dwordx4 v[68:71], v84, s[4:5]
	global_load_dwordx4 v[64:67], v83, s[4:5]
	global_load_dwordx4 v[56:59], v8, s[4:5]
	global_load_dwordx4 v[52:55], v9, s[4:5]
	global_load_dwordx4 v[48:51], v10, s[4:5]
	global_load_dwordx4 v[44:47], v11, s[4:5]
	global_load_dwordx4 v[40:43], v86, s[4:5]
	global_load_dwordx4 v[32:35], v85, s[4:5]
	global_load_dwordx4 v[28:31], v88, s[4:5]
	global_load_dwordx4 v[24:27], v87, s[4:5]
	global_load_dwordx4 v[20:23], v90, s[4:5]
	global_load_dwordx4 v[16:19], v89, s[4:5]
	global_load_dwordx4 v[4:7], v92, s[4:5]
	global_load_dwordx4 v[8:11], v91, s[4:5]
	global_load_dwordx4 v[132:135], v194, s[2:3] offset:16
	global_load_dwordx4 v[140:143], v194, s[2:3]
	v_lshrrev_b32_e32 v81, 2, v80
	v_and_b32_e32 v82, 14, v81
	v_and_b32_e32 v80, 8, v80
	v_lshlrev_b32_e32 v202, 1, v82
	v_cmp_eq_u32_e64 s[2:3], 0, v80
	v_lshlrev_b32_e32 v194, 1, v196
	v_mov_b32_e32 v204, v202
	s_waitcnt vmcnt(0)
	s_nop 0
	s_branch .LBB0_622

.LBB0_622:
	s_mov_b32 s9, s18
	s_cmp_lt_i32 s22, 8
	s_cselect_b32 s17, s22, s9
	s_waitcnt vmcnt(9)
	v_lshl_or_b32 v80, s17, 21, v196
	s_waitcnt vmcnt(1)
	v_lshl_add_u32 v81, v140, 7, v80
	v_lshl_add_u32 v82, v141, 7, v80
	s_mov_b32 s16, s23
	global_load_dwordx4 v[168:171], v81, s[4:5]
	global_load_dwordx4 v[164:167], v82, s[4:5]
	v_lshl_add_u32 v81, v142, 7, v80
	v_lshl_add_u32 v82, v143, 7, v80
	global_load_dwordx4 v[160:163], v81, s[4:5]
	global_load_dwordx4 v[156:159], v82, s[4:5]
	v_lshl_add_u32 v81, v132, 7, v80
	v_lshl_add_u32 v82, v133, 7, v80
	s_cselect_b32 s20, s8, s16
	global_load_dwordx4 v[152:155], v81, s[4:5]
	global_load_dwordx4 v[144:147], v82, s[4:5]
	v_lshl_add_u32 v81, v134, 7, v80
	v_lshl_add_u32 v82, v135, 7, v80
	s_ashr_i32 s21, s20, 31
	global_load_dwordx4 v[136:139], v81, s[4:5]
	global_load_dwordx4 v[128:131], v82, s[4:5]
	v_lshl_add_u32 v81, v108, 7, v80
	v_lshl_add_u32 v82, v109, 7, v80
	s_lshl_b64 s[20:21], s[20:21], 9
	global_load_dwordx4 v[124:127], v81, s[4:5]
	global_load_dwordx4 v[120:123], v82, s[4:5]
	v_lshl_add_u32 v81, v110, 7, v80
	v_lshl_add_u32 v82, v111, 7, v80
	s_cmp_lt_i32 s27, 8
	global_load_dwordx4 v[112:115], v81, s[4:5]
	global_load_dwordx4 v[104:107], v82, s[4:5]
	v_lshl_add_u32 v81, v100, 7, v80
	v_lshl_add_u32 v82, v101, 7, v80
	v_lshl_add_u64 v[100:101], v[198:199], 0, s[20:21]
	s_cselect_b64 s[20:21], -1, 0
	s_and_b64 s[24:25], s[20:21], exec
	s_cselect_b32 s24, s26, s16
	s_ashr_i32 s25, s24, 31
	global_load_dwordx4 v[96:99], v81, s[4:5]
	global_load_dwordx4 v[92:95], v82, s[4:5]
	v_lshl_add_u32 v81, v102, 7, v80
	v_lshl_add_u32 v80, v103, 7, v80
	s_lshl_b64 s[24:25], s[24:25], 9
	global_load_dwordx4 v[88:91], v81, s[4:5]
	s_nop 0
	global_load_dwordx4 v[80:83], v80, s[4:5]
	s_nop 0
	global_load_dwordx4 v[84:87], v[100:101], off offset:48
	global_load_dwordx4 v[116:119], v[100:101], off offset:32
	global_load_dwordx4 v[148:151], v[100:101], off offset:16
	global_load_dwordx4 v[172:175], v[100:101], off
	v_lshl_add_u64 v[100:101], v[200:201], 0, s[24:25]
	global_load_dwordx4 v[176:179], v[100:101], off offset:48
	global_load_dwordx4 v[180:183], v[100:101], off offset:32
	global_load_dwordx4 v[184:187], v[100:101], off offset:16
	global_load_dwordx4 v[188:191], v[100:101], off
	v_cvt_scalef32_pk_f16_fp8 v100, v76, 1.0
	v_cvt_scalef32_pk_f16_fp8 v76, v76, 1.0 op_sel:[1,0,0]
	v_cvt_scalef32_pk_f16_fp8 v101, v77, 1.0
	v_cvt_scalef32_pk_f16_fp8 v77, v77, 1.0 op_sel:[1,0,0]
	v_cvt_scalef32_pk_f16_fp8 v102, v78, 1.0
	v_cvt_scalef32_pk_f16_fp8 v78, v78, 1.0 op_sel:[1,0,0]
	v_cvt_scalef32_pk_f16_fp8 v103, v79, 1.0
	v_cvt_scalef32_pk_f16_fp8 v79, v79, 1.0 op_sel:[1,0,0]
	v_pk_fma_f16 v100, v100, v60, 0
	v_pk_fma_f16 v76, v76, v60, 0
	v_pk_fma_f16 v101, v101, v60, 0
	v_pk_fma_f16 v77, v77, v60, 0
	v_pk_fma_f16 v102, v102, v60, 0
	v_pk_fma_f16 v78, v78, v60, 0
	v_pk_fma_f16 v103, v103, v60, 0
	v_pk_fma_f16 v60, v79, v60, 0
	v_cvt_scalef32_pk_f16_fp8 v79, v72, 1.0
	v_cvt_scalef32_pk_f16_fp8 v72, v72, 1.0 op_sel:[1,0,0]
	v_pk_fma_f16 v72, v72, v61, v76
	v_cvt_scalef32_pk_f16_fp8 v76, v73, 1.0
	v_cvt_scalef32_pk_f16_fp8 v73, v73, 1.0 op_sel:[1,0,0]
	v_pk_fma_f16 v73, v73, v61, v77
	v_cvt_scalef32_pk_f16_fp8 v77, v74, 1.0
	v_cvt_scalef32_pk_f16_fp8 v74, v74, 1.0 op_sel:[1,0,0]
	v_pk_fma_f16 v74, v74, v61, v78
	v_cvt_scalef32_pk_f16_fp8 v78, v75, 1.0
	v_cvt_scalef32_pk_f16_fp8 v75, v75, 1.0 op_sel:[1,0,0]
	v_pk_fma_f16 v79, v79, v61, v100
	v_pk_fma_f16 v76, v76, v61, v101
	v_pk_fma_f16 v77, v77, v61, v102
	v_pk_fma_f16 v78, v78, v61, v103
	v_pk_fma_f16 v60, v75, v61, v60
	v_cvt_scalef32_pk_f16_fp8 v61, v68, 1.0
	v_cvt_scalef32_pk_f16_fp8 v68, v68, 1.0 op_sel:[1,0,0]
	v_pk_fma_f16 v68, v68, v62, v72
	v_cvt_scalef32_pk_f16_fp8 v72, v69, 1.0
	v_cvt_scalef32_pk_f16_fp8 v69, v69, 1.0 op_sel:[1,0,0]
	v_pk_fma_f16 v69, v69, v62, v73
	v_cvt_scalef32_pk_f16_fp8 v73, v70, 1.0
	v_cvt_scalef32_pk_f16_fp8 v70, v70, 1.0 op_sel:[1,0,0]
	v_pk_fma_f16 v70, v70, v62, v74
	v_cvt_scalef32_pk_f16_fp8 v74, v71, 1.0
	v_cvt_scalef32_pk_f16_fp8 v71, v71, 1.0 op_sel:[1,0,0]
	v_pk_fma_f16 v61, v61, v62, v79
	v_pk_fma_f16 v72, v72, v62, v76
	v_pk_fma_f16 v73, v73, v62, v77
	v_pk_fma_f16 v74, v74, v62, v78
	v_pk_fma_f16 v60, v71, v62, v60
	v_cvt_scalef32_pk_f16_fp8 v62, v64, 1.0
	v_pk_fma_f16 v61, v62, v63, v61
	v_cvt_scalef32_pk_f16_fp8 v62, v64, 1.0 op_sel:[1,0,0]
	v_cvt_scalef32_pk_f16_fp8 v64, v65, 1.0
	v_cvt_scalef32_pk_f16_fp8 v65, v65, 1.0 op_sel:[1,0,0]
	v_pk_fma_f16 v62, v62, v63, v68
	v_pk_fma_f16 v65, v65, v63, v69
	v_cvt_scalef32_pk_f16_fp8 v68, v66, 1.0
	v_cvt_scalef32_pk_f16_fp8 v66, v66, 1.0 op_sel:[1,0,0]
	v_cvt_scalef32_pk_f16_fp8 v69, v67, 1.0
	v_cvt_scalef32_pk_f16_fp8 v67, v67, 1.0 op_sel:[1,0,0]
	v_pk_fma_f16 v64, v64, v63, v72
	v_pk_fma_f16 v68, v68, v63, v73
	v_pk_fma_f16 v66, v66, v63, v70
	v_pk_fma_f16 v69, v69, v63, v74
	v_pk_fma_f16 v60, v67, v63, v60
	v_cvt_scalef32_pk_f16_fp8 v63, v56, 1.0
	v_cvt_scalef32_pk_f16_fp8 v56, v56, 1.0 op_sel:[1,0,0]
	v_pk_fma_f16 v56, v56, v36, v62
	v_cvt_scalef32_pk_f16_fp8 v62, v57, 1.0
	v_pk_fma_f16 v61, v63, v36, v61
	v_pk_fma_f16 v62, v62, v36, v64
	v_cvt_scalef32_pk_f16_fp8 v57, v57, 1.0 op_sel:[1,0,0]
	v_cvt_scalef32_pk_f16_fp8 v63, v58, 1.0
	v_cvt_scalef32_pk_f16_fp8 v58, v58, 1.0 op_sel:[1,0,0]
	v_cvt_scalef32_pk_f16_fp8 v64, v59, 1.0
	v_cvt_scalef32_pk_f16_fp8 v59, v59, 1.0 op_sel:[1,0,0]
	v_pk_fma_f16 v57, v57, v36, v65
	v_pk_fma_f16 v63, v63, v36, v68
	v_pk_fma_f16 v58, v58, v36, v66
	v_pk_fma_f16 v64, v64, v36, v69
	v_pk_fma_f16 v36, v59, v36, v60
	v_cvt_scalef32_pk_f16_fp8 v59, v52, 1.0
	v_cvt_scalef32_pk_f16_fp8 v52, v52, 1.0 op_sel:[1,0,0]
	v_pk_fma_f16 v52, v52, v37, v56
	v_cvt_scalef32_pk_f16_fp8 v56, v53, 1.0
	v_cvt_scalef32_pk_f16_fp8 v53, v53, 1.0 op_sel:[1,0,0]
	v_pk_fma_f16 v53, v53, v37, v57
	v_cvt_scalef32_pk_f16_fp8 v57, v54, 1.0
	v_cvt_scalef32_pk_f16_fp8 v54, v54, 1.0 op_sel:[1,0,0]
	v_pk_fma_f16 v54, v54, v37, v58
	v_cvt_scalef32_pk_f16_fp8 v58, v55, 1.0
	v_cvt_scalef32_pk_f16_fp8 v55, v55, 1.0 op_sel:[1,0,0]
	v_pk_fma_f16 v59, v59, v37, v61
	v_pk_fma_f16 v56, v56, v37, v62
	v_pk_fma_f16 v57, v57, v37, v63
	v_pk_fma_f16 v58, v58, v37, v64
	v_pk_fma_f16 v36, v55, v37, v36
	v_cvt_scalef32_pk_f16_fp8 v37, v48, 1.0
	v_cvt_scalef32_pk_f16_fp8 v48, v48, 1.0 op_sel:[1,0,0]
	v_pk_fma_f16 v48, v48, v38, v52
	v_cvt_scalef32_pk_f16_fp8 v52, v49, 1.0
	v_cvt_scalef32_pk_f16_fp8 v49, v49, 1.0 op_sel:[1,0,0]
	v_pk_fma_f16 v49, v49, v38, v53
	v_cvt_scalef32_pk_f16_fp8 v53, v50, 1.0
	v_cvt_scalef32_pk_f16_fp8 v50, v50, 1.0 op_sel:[1,0,0]
	v_pk_fma_f16 v50, v50, v38, v54
	v_cvt_scalef32_pk_f16_fp8 v54, v51, 1.0
	v_cvt_scalef32_pk_f16_fp8 v51, v51, 1.0 op_sel:[1,0,0]
	v_pk_fma_f16 v37, v37, v38, v59
	v_pk_fma_f16 v52, v52, v38, v56
	v_pk_fma_f16 v53, v53, v38, v57
	v_pk_fma_f16 v54, v54, v38, v58
	v_pk_fma_f16 v36, v51, v38, v36
	v_cvt_scalef32_pk_f16_fp8 v38, v44, 1.0
	v_pk_fma_f16 v37, v38, v39, v37
	v_cvt_scalef32_pk_f16_fp8 v38, v44, 1.0 op_sel:[1,0,0]
	v_cvt_scalef32_pk_f16_fp8 v44, v45, 1.0
	v_cvt_scalef32_pk_f16_fp8 v45, v45, 1.0 op_sel:[1,0,0]
	v_pk_fma_f16 v38, v38, v39, v48
	v_pk_fma_f16 v45, v45, v39, v49
	v_cvt_scalef32_pk_f16_fp8 v48, v46, 1.0
	v_cvt_scalef32_pk_f16_fp8 v46, v46, 1.0 op_sel:[1,0,0]
	v_cvt_scalef32_pk_f16_fp8 v49, v47, 1.0
	v_cvt_scalef32_pk_f16_fp8 v47, v47, 1.0 op_sel:[1,0,0]
	v_pk_fma_f16 v44, v44, v39, v52
	v_pk_fma_f16 v48, v48, v39, v53
	v_pk_fma_f16 v46, v46, v39, v50
	v_pk_fma_f16 v49, v49, v39, v54
	v_pk_fma_f16 v36, v47, v39, v36
	v_cvt_scalef32_pk_f16_fp8 v39, v40, 1.0
	v_pk_fma_f16 v37, v39, v12, v37
	v_cvt_scalef32_pk_f16_fp8 v39, v40, 1.0 op_sel:[1,0,0]
	v_pk_fma_f16 v38, v39, v12, v38
	v_cvt_scalef32_pk_f16_fp8 v39, v41, 1.0
	v_pk_fma_f16 v39, v39, v12, v44
	v_cvt_scalef32_pk_f16_fp8 v40, v41, 1.0 op_sel:[1,0,0]
	v_cvt_scalef32_pk_f16_fp8 v41, v42, 1.0
	v_cvt_scalef32_pk_f16_fp8 v42, v42, 1.0 op_sel:[1,0,0]
	v_cvt_scalef32_pk_f16_fp8 v44, v43, 1.0
	v_cvt_scalef32_pk_f16_fp8 v43, v43, 1.0 op_sel:[1,0,0]
	v_pk_fma_f16 v40, v40, v12, v45
	v_pk_fma_f16 v41, v41, v12, v48
	v_pk_fma_f16 v42, v42, v12, v46
	v_pk_fma_f16 v44, v44, v12, v49
	v_pk_fma_f16 v12, v43, v12, v36
	v_cvt_scalef32_pk_f16_fp8 v36, v32, 1.0
	v_pk_fma_f16 v36, v36, v13, v37
	v_cvt_scalef32_pk_f16_fp8 v32, v32, 1.0 op_sel:[1,0,0]
	v_cvt_scalef32_pk_f16_fp8 v37, v33, 1.0
	v_pk_fma_f16 v32, v32, v13, v38
	v_pk_fma_f16 v37, v37, v13, v39
	v_cvt_scalef32_pk_f16_fp8 v33, v33, 1.0 op_sel:[1,0,0]
	v_cvt_scalef32_pk_f16_fp8 v38, v34, 1.0
	v_cvt_scalef32_pk_f16_fp8 v34, v34, 1.0 op_sel:[1,0,0]
	v_cvt_scalef32_pk_f16_fp8 v39, v35, 1.0
	v_cvt_scalef32_pk_f16_fp8 v35, v35, 1.0 op_sel:[1,0,0]
	v_pk_fma_f16 v33, v33, v13, v40
	v_pk_fma_f16 v38, v38, v13, v41
	v_pk_fma_f16 v34, v34, v13, v42
	v_pk_fma_f16 v39, v39, v13, v44
	v_pk_fma_f16 v12, v35, v13, v12
	v_cvt_scalef32_pk_f16_fp8 v13, v28, 1.0
	v_cvt_scalef32_pk_f16_fp8 v28, v28, 1.0 op_sel:[1,0,0]
	v_pk_fma_f16 v28, v28, v14, v32
	v_cvt_scalef32_pk_f16_fp8 v32, v29, 1.0
	v_cvt_scalef32_pk_f16_fp8 v29, v29, 1.0 op_sel:[1,0,0]
	v_pk_fma_f16 v29, v29, v14, v33
	v_cvt_scalef32_pk_f16_fp8 v33, v30, 1.0
	v_cvt_scalef32_pk_f16_fp8 v30, v30, 1.0 op_sel:[1,0,0]
	v_pk_fma_f16 v30, v30, v14, v34
	v_cvt_scalef32_pk_f16_fp8 v34, v31, 1.0
	v_cvt_scalef32_pk_f16_fp8 v31, v31, 1.0 op_sel:[1,0,0]
	v_pk_fma_f16 v13, v13, v14, v36
	v_pk_fma_f16 v32, v32, v14, v37
	v_pk_fma_f16 v33, v33, v14, v38
	v_pk_fma_f16 v34, v34, v14, v39
	v_pk_fma_f16 v12, v31, v14, v12
	v_cvt_scalef32_pk_f16_fp8 v14, v24, 1.0
	v_pk_fma_f16 v13, v14, v15, v13
	v_cvt_scalef32_pk_f16_fp8 v14, v24, 1.0 op_sel:[1,0,0]
	v_cvt_scalef32_pk_f16_fp8 v24, v25, 1.0
	v_cvt_scalef32_pk_f16_fp8 v25, v25, 1.0 op_sel:[1,0,0]
	v_pk_fma_f16 v14, v14, v15, v28
	v_pk_fma_f16 v25, v25, v15, v29
	v_cvt_scalef32_pk_f16_fp8 v28, v26, 1.0
	v_cvt_scalef32_pk_f16_fp8 v26, v26, 1.0 op_sel:[1,0,0]
	v_cvt_scalef32_pk_f16_fp8 v29, v27, 1.0
	v_cvt_scalef32_pk_f16_fp8 v27, v27, 1.0 op_sel:[1,0,0]
	v_pk_fma_f16 v24, v24, v15, v32
	v_pk_fma_f16 v28, v28, v15, v33
	v_pk_fma_f16 v26, v26, v15, v30
	v_pk_fma_f16 v29, v29, v15, v34
	v_pk_fma_f16 v12, v27, v15, v12
	v_cvt_scalef32_pk_f16_fp8 v15, v20, 1.0
	v_pk_fma_f16 v13, v15, v0, v13
	v_cvt_scalef32_pk_f16_fp8 v15, v20, 1.0 op_sel:[1,0,0]
	v_pk_fma_f16 v14, v15, v0, v14
	v_cvt_scalef32_pk_f16_fp8 v15, v21, 1.0
	v_pk_fma_f16 v15, v15, v0, v24
	v_cvt_scalef32_pk_f16_fp8 v20, v21, 1.0 op_sel:[1,0,0]
	v_cvt_scalef32_pk_f16_fp8 v21, v22, 1.0
	v_cvt_scalef32_pk_f16_fp8 v22, v22, 1.0 op_sel:[1,0,0]
	v_cvt_scalef32_pk_f16_fp8 v24, v23, 1.0
	v_cvt_scalef32_pk_f16_fp8 v23, v23, 1.0 op_sel:[1,0,0]
	v_pk_fma_f16 v20, v20, v0, v25
	v_pk_fma_f16 v21, v21, v0, v28
	v_pk_fma_f16 v22, v22, v0, v26
	v_pk_fma_f16 v24, v24, v0, v29
	v_pk_fma_f16 v0, v23, v0, v12
	v_cvt_scalef32_pk_f16_fp8 v12, v16, 1.0
	v_pk_fma_f16 v12, v12, v1, v13
	v_cvt_scalef32_pk_f16_fp8 v13, v16, 1.0 op_sel:[1,0,0]
	v_pk_fma_f16 v13, v13, v1, v14
	v_cvt_scalef32_pk_f16_fp8 v14, v17, 1.0
	v_pk_fma_f16 v14, v14, v1, v15
	v_cvt_scalef32_pk_f16_fp8 v15, v17, 1.0 op_sel:[1,0,0]
	v_cvt_scalef32_pk_f16_fp8 v16, v18, 1.0
	v_cvt_scalef32_pk_f16_fp8 v17, v18, 1.0 op_sel:[1,0,0]
	v_cvt_scalef32_pk_f16_fp8 v18, v19, 1.0
	v_cvt_scalef32_pk_f16_fp8 v19, v19, 1.0 op_sel:[1,0,0]
	v_pk_fma_f16 v15, v15, v1, v20
	v_pk_fma_f16 v16, v16, v1, v21
	v_pk_fma_f16 v17, v17, v1, v22
	v_pk_fma_f16 v18, v18, v1, v24
	v_pk_fma_f16 v0, v19, v1, v0
	v_cvt_scalef32_pk_f16_fp8 v1, v4, 1.0
	v_pk_fma_f16 v1, v1, v2, v12
	v_cvt_scalef32_pk_f16_fp8 v4, v4, 1.0 op_sel:[1,0,0]
	v_cvt_scalef32_pk_f16_fp8 v12, v5, 1.0
	v_pk_fma_f16 v4, v4, v2, v13
	v_pk_fma_f16 v12, v12, v2, v14
	v_cvt_scalef32_pk_f16_fp8 v5, v5, 1.0 op_sel:[1,0,0]
	v_cvt_scalef32_pk_f16_fp8 v13, v6, 1.0
	v_cvt_scalef32_pk_f16_fp8 v6, v6, 1.0 op_sel:[1,0,0]
	v_cvt_scalef32_pk_f16_fp8 v14, v7, 1.0
	v_cvt_scalef32_pk_f16_fp8 v7, v7, 1.0 op_sel:[1,0,0]
	v_pk_fma_f16 v5, v5, v2, v15
	v_pk_fma_f16 v13, v13, v2, v16
	v_pk_fma_f16 v6, v6, v2, v17
	v_pk_fma_f16 v14, v14, v2, v18
	v_pk_fma_f16 v0, v7, v2, v0
	v_cvt_scalef32_pk_f16_fp8 v2, v8, 1.0
	v_pk_fma_f16 v1, v2, v3, v1
	v_cvt_scalef32_pk_f16_fp8 v2, v8, 1.0 op_sel:[1,0,0]
	v_cvt_scalef32_pk_f16_fp8 v7, v9, 1.0 op_sel:[1,0,0]
	v_cvt_scalef32_pk_f16_fp8 v8, v10, 1.0 op_sel:[1,0,0]
	v_pk_fma_f16 v2, v2, v3, v4
	v_cvt_scalef32_pk_f16_fp8 v4, v9, 1.0
	v_pk_fma_f16 v5, v7, v3, v5
	v_cvt_scalef32_pk_f16_fp8 v7, v10, 1.0
	v_pk_fma_f16 v6, v8, v3, v6
	v_cvt_scalef32_pk_f16_fp8 v8, v11, 1.0
	v_cvt_scalef32_pk_f16_fp8 v9, v11, 1.0 op_sel:[1,0,0]
	v_pk_fma_f16 v4, v4, v3, v12
	v_pk_fma_f16 v7, v7, v3, v13
	v_pk_fma_f16 v8, v8, v3, v14
	v_pk_fma_f16 v0, v9, v3, v0
	v_permlane32_swap_b32_e32 v1, v7
	v_permlane32_swap_b32_e32 v2, v6
	v_permlane32_swap_b32_e32 v4, v8
	v_permlane32_swap_b32_e32 v5, v0
	v_pk_add_f16 v1, v1, v7
	v_pk_add_f16 v2, v2, v6
	v_pk_add_f16 v3, v4, v8
	v_pk_add_f16 v0, v5, v0
	s_nop 0
	v_permlane16_swap_b32_e32 v1, v3
	v_permlane16_swap_b32_e32 v2, v0
	v_pk_add_f16 v1, v1, v3
	v_pk_add_f16 v0, v2, v0
	s_ashr_i32 s17, s16, 31
	v_cndmask_b32_e64 v2, v1, v0, s[2:3]
	v_cndmask_b32_e64 v0, v0, v1, s[2:3]
	s_lshl_b64 s[16:17], s[16:17], 11
	v_mov_b32_dpp v1, v2 row_ror:8 row_mask:0xf bank_mask:0xf bound_ctrl:1
	v_pk_add_f16 v1, v1, v0
	s_add_u32 s24, s14, s16
	v_cvt_f32_f16_e32 v0, v1
	v_cvt_f32_f16_sdwa v1, v1 dst_sel:DWORD dst_unused:UNUSED_PAD src0_sel:WORD_1
	s_addc_u32 s25, s15, s17
	s_lshl_b32 s16, s9, 7
	s_ashr_i32 s17, s16, 31
	v_pk_mul_f32 v[0:1], v[0:1], s[10:11] op_sel_hi:[1,0]
	s_lshl_b64 s[16:17], s[16:17], 1
	v_and_b32_sdwa v3, v0, v208 dst_sel:DWORD dst_unused:UNUSED_PAD src0_sel:WORD_1 src1_sel:DWORD
	v_and_b32_sdwa v2, v1, v208 dst_sel:DWORD dst_unused:UNUSED_PAD src0_sel:WORD_1 src1_sel:DWORD
	v_add3_u32 v0, v0, v3, s7
	s_add_u32 s16, s24, s16
	v_add3_u32 v1, v1, v2, s7
	v_lshrrev_b32_e32 v0, 16, v0
	s_addc_u32 s17, s25, s17
	v_and_or_b32 v2, v1, s11, v0
	v_lshl_add_u64 v[0:1], s[16:17], 0, v[194:195]
	s_mov_b32 s18, s27
	s_mov_b32 s23, s26
	v_lshl_add_u64 v[0:1], v[0:1], 0, v[204:205]
	s_cmp_gt_i32 s22, 7
	s_mov_b64 s[16:17], -1
	global_store_dword v[0:1], v2, off
	s_cbranch_scc1 .LBB0_621
	s_add_i32 s9, s23, s19
	s_cmpk_gt_i32 s9, 0x3fff
	s_cselect_b32 s25, s33, 0
	s_cselect_b32 s24, s6, s9
	s_add_i32 s25, s25, s18
	s_and_b64 s[16:17], s[20:21], exec
	s_cselect_b32 s9, s18, s22
	v_lshl_or_b32 v0, s9, 21, v196
	s_waitcnt vmcnt(1)
	v_lshl_add_u32 v1, v188, 7, v0
	s_cselect_b32 s16, s23, s8
	v_lshl_add_u32 v2, v189, 7, v0
	global_load_dwordx4 v[76:79], v1, s[4:5]
	global_load_dwordx4 v[72:75], v2, s[4:5]
	v_lshl_add_u32 v1, v190, 7, v0
	s_ashr_i32 s17, s16, 31
	v_lshl_add_u32 v2, v191, 7, v0
	global_load_dwordx4 v[68:71], v1, s[4:5]
	global_load_dwordx4 v[64:67], v2, s[4:5]
	v_lshl_add_u32 v1, v184, 7, v0
	s_lshl_b64 s[16:17], s[16:17], 9
	v_lshl_add_u32 v2, v185, 7, v0
	global_load_dwordx4 v[56:59], v1, s[4:5]
	global_load_dwordx4 v[52:55], v2, s[4:5]
	v_lshl_add_u32 v1, v186, 7, v0
	s_cmp_lt_i32 s25, 8
	v_lshl_add_u32 v2, v187, 7, v0
	global_load_dwordx4 v[48:51], v1, s[4:5]
	global_load_dwordx4 v[44:47], v2, s[4:5]
	v_lshl_add_u32 v1, v180, 7, v0
	v_lshl_add_u64 v[60:61], v[198:199], 0, s[16:17]
	s_cselect_b32 s16, s24, s8
	v_lshl_add_u32 v2, v181, 7, v0
	global_load_dwordx4 v[40:43], v1, s[4:5]
	global_load_dwordx4 v[32:35], v2, s[4:5]
	v_lshl_add_u32 v1, v182, 7, v0
	s_ashr_i32 s17, s16, 31
	v_lshl_add_u32 v2, v183, 7, v0
	global_load_dwordx4 v[28:31], v1, s[4:5]
	global_load_dwordx4 v[24:27], v2, s[4:5]
	v_lshl_add_u32 v1, v176, 7, v0
	s_lshl_b64 s[16:17], s[16:17], 9
	v_lshl_add_u32 v2, v177, 7, v0
	global_load_dwordx4 v[20:23], v1, s[4:5]
	global_load_dwordx4 v[16:19], v2, s[4:5]
	v_lshl_add_u32 v1, v178, 7, v0
	v_lshl_add_u32 v0, v179, 7, v0
	v_lshl_add_u64 v[140:141], v[200:201], 0, s[16:17]
	global_load_dwordx4 v[4:7], v1, s[4:5]
	global_load_dwordx4 v[8:11], v0, s[4:5]
	s_nop 0
	global_load_dwordx4 v[0:3], v[60:61], off offset:48
	global_load_dwordx4 v[12:15], v[60:61], off offset:32
	global_load_dwordx4 v[36:39], v[60:61], off offset:16
	s_nop 0
	global_load_dwordx4 v[60:63], v[60:61], off
	s_nop 0
	global_load_dwordx4 v[100:103], v[140:141], off offset:48
	global_load_dwordx4 v[108:111], v[140:141], off offset:32
	global_load_dwordx4 v[132:135], v[140:141], off offset:16
	s_nop 0
	global_load_dwordx4 v[140:143], v[140:141], off
	v_cvt_scalef32_pk_f16_fp8 v176, v168, 1.0
	v_cvt_scalef32_pk_f16_fp8 v168, v168, 1.0 op_sel:[1,0,0]
	v_cvt_scalef32_pk_f16_fp8 v177, v169, 1.0
	v_cvt_scalef32_pk_f16_fp8 v169, v169, 1.0 op_sel:[1,0,0]
	v_cvt_scalef32_pk_f16_fp8 v178, v170, 1.0
	v_cvt_scalef32_pk_f16_fp8 v170, v170, 1.0 op_sel:[1,0,0]
	v_cvt_scalef32_pk_f16_fp8 v179, v171, 1.0
	v_cvt_scalef32_pk_f16_fp8 v171, v171, 1.0 op_sel:[1,0,0]
	v_pk_fma_f16 v176, v176, v172, 0
	v_pk_fma_f16 v168, v168, v172, 0
	v_pk_fma_f16 v177, v177, v172, 0
	v_pk_fma_f16 v169, v169, v172, 0
	v_pk_fma_f16 v178, v178, v172, 0
	v_pk_fma_f16 v170, v170, v172, 0
	v_pk_fma_f16 v179, v179, v172, 0
	v_pk_fma_f16 v171, v171, v172, 0
	v_cvt_scalef32_pk_f16_fp8 v172, v164, 1.0
	v_cvt_scalef32_pk_f16_fp8 v164, v164, 1.0 op_sel:[1,0,0]
	v_pk_fma_f16 v164, v164, v173, v168
	v_cvt_scalef32_pk_f16_fp8 v168, v165, 1.0
	v_cvt_scalef32_pk_f16_fp8 v165, v165, 1.0 op_sel:[1,0,0]
	v_pk_fma_f16 v165, v165, v173, v169
	v_cvt_scalef32_pk_f16_fp8 v169, v166, 1.0
	v_cvt_scalef32_pk_f16_fp8 v166, v166, 1.0 op_sel:[1,0,0]
	v_pk_fma_f16 v166, v166, v173, v170
	v_cvt_scalef32_pk_f16_fp8 v170, v167, 1.0
	v_cvt_scalef32_pk_f16_fp8 v167, v167, 1.0 op_sel:[1,0,0]
	v_pk_fma_f16 v167, v167, v173, v171
	v_cvt_scalef32_pk_f16_fp8 v171, v160, 1.0
	v_cvt_scalef32_pk_f16_fp8 v160, v160, 1.0 op_sel:[1,0,0]
	v_pk_fma_f16 v160, v160, v174, v164
	v_cvt_scalef32_pk_f16_fp8 v164, v161, 1.0
	v_cvt_scalef32_pk_f16_fp8 v161, v161, 1.0 op_sel:[1,0,0]
	v_pk_fma_f16 v161, v161, v174, v165
	v_cvt_scalef32_pk_f16_fp8 v165, v162, 1.0
	v_cvt_scalef32_pk_f16_fp8 v162, v162, 1.0 op_sel:[1,0,0]
	v_pk_fma_f16 v162, v162, v174, v166
	v_cvt_scalef32_pk_f16_fp8 v166, v163, 1.0
	v_cvt_scalef32_pk_f16_fp8 v163, v163, 1.0 op_sel:[1,0,0]
	v_pk_fma_f16 v163, v163, v174, v167
	v_cvt_scalef32_pk_f16_fp8 v167, v156, 1.0
	v_cvt_scalef32_pk_f16_fp8 v156, v156, 1.0 op_sel:[1,0,0]
	v_pk_fma_f16 v156, v156, v175, v160
	v_cvt_scalef32_pk_f16_fp8 v160, v157, 1.0
	v_cvt_scalef32_pk_f16_fp8 v157, v157, 1.0 op_sel:[1,0,0]
	v_pk_fma_f16 v157, v157, v175, v161
	v_cvt_scalef32_pk_f16_fp8 v161, v158, 1.0
	v_cvt_scalef32_pk_f16_fp8 v158, v158, 1.0 op_sel:[1,0,0]
	v_pk_fma_f16 v158, v158, v175, v162
	v_cvt_scalef32_pk_f16_fp8 v162, v159, 1.0
	v_cvt_scalef32_pk_f16_fp8 v159, v159, 1.0 op_sel:[1,0,0]
	v_pk_fma_f16 v159, v159, v175, v163
	v_cvt_scalef32_pk_f16_fp8 v163, v152, 1.0
	v_cvt_scalef32_pk_f16_fp8 v152, v152, 1.0 op_sel:[1,0,0]
	v_pk_fma_f16 v172, v172, v173, v176
	v_pk_fma_f16 v168, v168, v173, v177
	v_pk_fma_f16 v169, v169, v173, v178
	v_pk_fma_f16 v170, v170, v173, v179
	v_pk_fma_f16 v152, v152, v148, v156
	v_cvt_scalef32_pk_f16_fp8 v156, v153, 1.0
	v_cvt_scalef32_pk_f16_fp8 v153, v153, 1.0 op_sel:[1,0,0]
	v_pk_fma_f16 v171, v171, v174, v172
	v_pk_fma_f16 v164, v164, v174, v168
	v_pk_fma_f16 v165, v165, v174, v169
	v_pk_fma_f16 v166, v166, v174, v170
	v_pk_fma_f16 v153, v153, v148, v157
	v_cvt_scalef32_pk_f16_fp8 v157, v154, 1.0
	v_cvt_scalef32_pk_f16_fp8 v154, v154, 1.0 op_sel:[1,0,0]
	v_pk_fma_f16 v167, v167, v175, v171
	v_pk_fma_f16 v160, v160, v175, v164
	v_pk_fma_f16 v161, v161, v175, v165
	v_pk_fma_f16 v162, v162, v175, v166
	v_pk_fma_f16 v154, v154, v148, v158
	v_cvt_scalef32_pk_f16_fp8 v158, v155, 1.0
	v_cvt_scalef32_pk_f16_fp8 v155, v155, 1.0 op_sel:[1,0,0]
	v_pk_fma_f16 v163, v163, v148, v167
	v_pk_fma_f16 v156, v156, v148, v160
	v_pk_fma_f16 v157, v157, v148, v161
	v_pk_fma_f16 v158, v158, v148, v162
	v_pk_fma_f16 v148, v155, v148, v159
	v_cvt_scalef32_pk_f16_fp8 v155, v144, 1.0
	v_cvt_scalef32_pk_f16_fp8 v144, v144, 1.0 op_sel:[1,0,0]
	v_pk_fma_f16 v144, v144, v149, v152
	v_cvt_scalef32_pk_f16_fp8 v152, v145, 1.0
	v_cvt_scalef32_pk_f16_fp8 v145, v145, 1.0 op_sel:[1,0,0]
	v_pk_fma_f16 v145, v145, v149, v153
	v_cvt_scalef32_pk_f16_fp8 v153, v146, 1.0
	v_cvt_scalef32_pk_f16_fp8 v146, v146, 1.0 op_sel:[1,0,0]
	v_pk_fma_f16 v146, v146, v149, v154
	v_cvt_scalef32_pk_f16_fp8 v154, v147, 1.0
	v_cvt_scalef32_pk_f16_fp8 v147, v147, 1.0 op_sel:[1,0,0]
	v_pk_fma_f16 v147, v147, v149, v148
	v_cvt_scalef32_pk_f16_fp8 v148, v136, 1.0
	v_cvt_scalef32_pk_f16_fp8 v136, v136, 1.0 op_sel:[1,0,0]
	v_pk_fma_f16 v136, v136, v150, v144
	v_cvt_scalef32_pk_f16_fp8 v144, v137, 1.0
	v_cvt_scalef32_pk_f16_fp8 v137, v137, 1.0 op_sel:[1,0,0]
	v_pk_fma_f16 v137, v137, v150, v145
	v_cvt_scalef32_pk_f16_fp8 v145, v138, 1.0
	v_cvt_scalef32_pk_f16_fp8 v138, v138, 1.0 op_sel:[1,0,0]
	v_pk_fma_f16 v138, v138, v150, v146
	v_cvt_scalef32_pk_f16_fp8 v146, v139, 1.0
	v_cvt_scalef32_pk_f16_fp8 v139, v139, 1.0 op_sel:[1,0,0]
	v_pk_fma_f16 v139, v139, v150, v147
	v_cvt_scalef32_pk_f16_fp8 v147, v128, 1.0
	v_cvt_scalef32_pk_f16_fp8 v128, v128, 1.0 op_sel:[1,0,0]
	v_pk_fma_f16 v128, v128, v151, v136
	v_cvt_scalef32_pk_f16_fp8 v136, v129, 1.0
	v_cvt_scalef32_pk_f16_fp8 v129, v129, 1.0 op_sel:[1,0,0]
	v_pk_fma_f16 v129, v129, v151, v137
	v_cvt_scalef32_pk_f16_fp8 v137, v130, 1.0
	v_cvt_scalef32_pk_f16_fp8 v130, v130, 1.0 op_sel:[1,0,0]
	v_pk_fma_f16 v130, v130, v151, v138
	v_cvt_scalef32_pk_f16_fp8 v138, v131, 1.0
	v_cvt_scalef32_pk_f16_fp8 v131, v131, 1.0 op_sel:[1,0,0]
	v_pk_fma_f16 v131, v131, v151, v139
	v_cvt_scalef32_pk_f16_fp8 v139, v124, 1.0
	v_cvt_scalef32_pk_f16_fp8 v124, v124, 1.0 op_sel:[1,0,0]
	v_pk_fma_f16 v155, v155, v149, v163
	v_pk_fma_f16 v152, v152, v149, v156
	v_pk_fma_f16 v153, v153, v149, v157
	v_pk_fma_f16 v154, v154, v149, v158
	v_pk_fma_f16 v124, v124, v116, v128
	v_cvt_scalef32_pk_f16_fp8 v128, v125, 1.0
	v_cvt_scalef32_pk_f16_fp8 v125, v125, 1.0 op_sel:[1,0,0]
	v_pk_fma_f16 v148, v148, v150, v155
	v_pk_fma_f16 v144, v144, v150, v152
	v_pk_fma_f16 v145, v145, v150, v153
	v_pk_fma_f16 v146, v146, v150, v154
	v_pk_fma_f16 v125, v125, v116, v129
	v_cvt_scalef32_pk_f16_fp8 v129, v126, 1.0
	v_cvt_scalef32_pk_f16_fp8 v126, v126, 1.0 op_sel:[1,0,0]
	v_pk_fma_f16 v147, v147, v151, v148
	v_pk_fma_f16 v136, v136, v151, v144
	v_pk_fma_f16 v137, v137, v151, v145
	v_pk_fma_f16 v138, v138, v151, v146
	v_pk_fma_f16 v126, v126, v116, v130
	v_cvt_scalef32_pk_f16_fp8 v130, v127, 1.0
	v_cvt_scalef32_pk_f16_fp8 v127, v127, 1.0 op_sel:[1,0,0]
	v_pk_fma_f16 v139, v139, v116, v147
	v_pk_fma_f16 v128, v128, v116, v136
	v_pk_fma_f16 v129, v129, v116, v137
	v_pk_fma_f16 v130, v130, v116, v138
	v_pk_fma_f16 v116, v127, v116, v131
	v_cvt_scalef32_pk_f16_fp8 v127, v120, 1.0
	v_cvt_scalef32_pk_f16_fp8 v120, v120, 1.0 op_sel:[1,0,0]
	v_pk_fma_f16 v120, v120, v117, v124
	v_cvt_scalef32_pk_f16_fp8 v124, v121, 1.0
	v_cvt_scalef32_pk_f16_fp8 v121, v121, 1.0 op_sel:[1,0,0]
	v_pk_fma_f16 v121, v121, v117, v125
	v_cvt_scalef32_pk_f16_fp8 v125, v122, 1.0
	v_cvt_scalef32_pk_f16_fp8 v122, v122, 1.0 op_sel:[1,0,0]
	v_pk_fma_f16 v122, v122, v117, v126
	v_cvt_scalef32_pk_f16_fp8 v126, v123, 1.0
	v_cvt_scalef32_pk_f16_fp8 v123, v123, 1.0 op_sel:[1,0,0]
	v_pk_fma_f16 v127, v127, v117, v139
	v_pk_fma_f16 v124, v124, v117, v128
	v_pk_fma_f16 v125, v125, v117, v129
	v_pk_fma_f16 v126, v126, v117, v130
	v_pk_fma_f16 v116, v123, v117, v116
	v_cvt_scalef32_pk_f16_fp8 v117, v112, 1.0
	v_cvt_scalef32_pk_f16_fp8 v112, v112, 1.0 op_sel:[1,0,0]
	v_pk_fma_f16 v112, v112, v118, v120
	v_cvt_scalef32_pk_f16_fp8 v120, v113, 1.0
	v_cvt_scalef32_pk_f16_fp8 v113, v113, 1.0 op_sel:[1,0,0]
	v_pk_fma_f16 v113, v113, v118, v121
	v_cvt_scalef32_pk_f16_fp8 v121, v114, 1.0
	v_cvt_scalef32_pk_f16_fp8 v114, v114, 1.0 op_sel:[1,0,0]
	v_pk_fma_f16 v114, v114, v118, v122
	v_cvt_scalef32_pk_f16_fp8 v122, v115, 1.0
	v_cvt_scalef32_pk_f16_fp8 v115, v115, 1.0 op_sel:[1,0,0]
	v_pk_fma_f16 v115, v115, v118, v116
	v_cvt_scalef32_pk_f16_fp8 v116, v104, 1.0
	v_cvt_scalef32_pk_f16_fp8 v104, v104, 1.0 op_sel:[1,0,0]
	v_pk_fma_f16 v104, v104, v119, v112
	v_cvt_scalef32_pk_f16_fp8 v112, v105, 1.0
	v_cvt_scalef32_pk_f16_fp8 v105, v105, 1.0 op_sel:[1,0,0]
	v_pk_fma_f16 v105, v105, v119, v113
	v_cvt_scalef32_pk_f16_fp8 v113, v106, 1.0
	v_cvt_scalef32_pk_f16_fp8 v106, v106, 1.0 op_sel:[1,0,0]
	v_pk_fma_f16 v106, v106, v119, v114
	v_cvt_scalef32_pk_f16_fp8 v114, v107, 1.0
	v_cvt_scalef32_pk_f16_fp8 v107, v107, 1.0 op_sel:[1,0,0]
	v_pk_fma_f16 v107, v107, v119, v115
	v_cvt_scalef32_pk_f16_fp8 v115, v96, 1.0
	v_cvt_scalef32_pk_f16_fp8 v96, v96, 1.0 op_sel:[1,0,0]
	v_pk_fma_f16 v96, v96, v84, v104
	v_cvt_scalef32_pk_f16_fp8 v104, v97, 1.0
	v_cvt_scalef32_pk_f16_fp8 v97, v97, 1.0 op_sel:[1,0,0]
	v_pk_fma_f16 v117, v117, v118, v127
	v_pk_fma_f16 v120, v120, v118, v124
	v_pk_fma_f16 v121, v121, v118, v125
	v_pk_fma_f16 v122, v122, v118, v126
	v_pk_fma_f16 v97, v97, v84, v105
	v_cvt_scalef32_pk_f16_fp8 v105, v98, 1.0
	v_cvt_scalef32_pk_f16_fp8 v98, v98, 1.0 op_sel:[1,0,0]
	v_pk_fma_f16 v116, v116, v119, v117
	v_pk_fma_f16 v112, v112, v119, v120
	v_pk_fma_f16 v113, v113, v119, v121
	v_pk_fma_f16 v114, v114, v119, v122
	v_pk_fma_f16 v98, v98, v84, v106
	v_cvt_scalef32_pk_f16_fp8 v106, v99, 1.0
	v_cvt_scalef32_pk_f16_fp8 v99, v99, 1.0 op_sel:[1,0,0]
	v_pk_fma_f16 v115, v115, v84, v116
	v_pk_fma_f16 v104, v104, v84, v112
	v_pk_fma_f16 v105, v105, v84, v113
	v_pk_fma_f16 v106, v106, v84, v114
	v_pk_fma_f16 v84, v99, v84, v107
	v_cvt_scalef32_pk_f16_fp8 v99, v92, 1.0
	v_cvt_scalef32_pk_f16_fp8 v92, v92, 1.0 op_sel:[1,0,0]
	v_pk_fma_f16 v92, v92, v85, v96
	v_cvt_scalef32_pk_f16_fp8 v96, v93, 1.0
	v_cvt_scalef32_pk_f16_fp8 v93, v93, 1.0 op_sel:[1,0,0]
	v_pk_fma_f16 v93, v93, v85, v97
	v_cvt_scalef32_pk_f16_fp8 v97, v94, 1.0
	v_cvt_scalef32_pk_f16_fp8 v94, v94, 1.0 op_sel:[1,0,0]
	v_pk_fma_f16 v94, v94, v85, v98
	v_cvt_scalef32_pk_f16_fp8 v98, v95, 1.0
	v_cvt_scalef32_pk_f16_fp8 v95, v95, 1.0 op_sel:[1,0,0]
	v_pk_fma_f16 v99, v99, v85, v115
	v_pk_fma_f16 v96, v96, v85, v104
	v_pk_fma_f16 v97, v97, v85, v105
	v_pk_fma_f16 v98, v98, v85, v106
	v_pk_fma_f16 v84, v95, v85, v84
	v_cvt_scalef32_pk_f16_fp8 v85, v88, 1.0
	v_cvt_scalef32_pk_f16_fp8 v88, v88, 1.0 op_sel:[1,0,0]
	v_pk_fma_f16 v88, v88, v86, v92
	v_cvt_scalef32_pk_f16_fp8 v92, v89, 1.0
	v_cvt_scalef32_pk_f16_fp8 v89, v89, 1.0 op_sel:[1,0,0]
	v_pk_fma_f16 v89, v89, v86, v93
	v_cvt_scalef32_pk_f16_fp8 v93, v90, 1.0
	v_cvt_scalef32_pk_f16_fp8 v90, v90, 1.0 op_sel:[1,0,0]
	v_pk_fma_f16 v90, v90, v86, v94
	v_cvt_scalef32_pk_f16_fp8 v94, v91, 1.0
	v_cvt_scalef32_pk_f16_fp8 v91, v91, 1.0 op_sel:[1,0,0]
	v_pk_fma_f16 v85, v85, v86, v99
	v_pk_fma_f16 v92, v92, v86, v96
	v_pk_fma_f16 v93, v93, v86, v97
	v_pk_fma_f16 v94, v94, v86, v98
	v_pk_fma_f16 v84, v91, v86, v84
	v_cvt_scalef32_pk_f16_fp8 v86, v80, 1.0
	v_pk_fma_f16 v85, v86, v87, v85
	v_cvt_scalef32_pk_f16_fp8 v80, v80, 1.0 op_sel:[1,0,0]
	v_cvt_scalef32_pk_f16_fp8 v86, v81, 1.0
	v_cvt_scalef32_pk_f16_fp8 v81, v81, 1.0 op_sel:[1,0,0]
	v_pk_fma_f16 v80, v80, v87, v88
	v_pk_fma_f16 v81, v81, v87, v89
	v_cvt_scalef32_pk_f16_fp8 v88, v82, 1.0
	v_cvt_scalef32_pk_f16_fp8 v82, v82, 1.0 op_sel:[1,0,0]
	v_cvt_scalef32_pk_f16_fp8 v89, v83, 1.0
	v_cvt_scalef32_pk_f16_fp8 v83, v83, 1.0 op_sel:[1,0,0]
	v_pk_fma_f16 v86, v86, v87, v92
	v_pk_fma_f16 v88, v88, v87, v93
	v_pk_fma_f16 v82, v82, v87, v90
	v_pk_fma_f16 v89, v89, v87, v94
	v_pk_fma_f16 v83, v83, v87, v84
	v_permlane32_swap_b32_e32 v85, v88
	v_permlane32_swap_b32_e32 v80, v82
	v_permlane32_swap_b32_e32 v86, v89
	v_permlane32_swap_b32_e32 v81, v83
	v_pk_add_f16 v84, v85, v88
	v_pk_add_f16 v80, v80, v82
	v_pk_add_f16 v82, v86, v89
	v_pk_add_f16 v81, v81, v83
	s_nop 0
	v_permlane16_swap_b32_e32 v84, v82
	v_permlane16_swap_b32_e32 v80, v81
	v_pk_add_f16 v82, v84, v82
	v_pk_add_f16 v80, v80, v81
	s_ashr_i32 s9, s8, 31
	v_cndmask_b32_e64 v81, v82, v80, s[2:3]
	v_cndmask_b32_e64 v80, v80, v82, s[2:3]
	s_lshl_b64 s[8:9], s[8:9], 11
	v_mov_b32_dpp v81, v81 row_ror:8 row_mask:0xf bank_mask:0xf bound_ctrl:1
	v_pk_add_f16 v81, v81, v80
	s_add_u32 s16, s14, s8
	v_cvt_f32_f16_e32 v80, v81
	v_cvt_f32_f16_sdwa v81, v81 dst_sel:DWORD dst_unused:UNUSED_PAD src0_sel:WORD_1
	s_addc_u32 s17, s15, s9
	s_lshl_b32 s8, s22, 7
	s_ashr_i32 s9, s8, 31
	v_pk_mul_f32 v[80:81], v[80:81], s[10:11] op_sel_hi:[1,0]
	s_lshl_b64 s[8:9], s[8:9], 1
	v_and_b32_sdwa v83, v80, v208 dst_sel:DWORD dst_unused:UNUSED_PAD src0_sel:WORD_1 src1_sel:DWORD
	v_and_b32_sdwa v82, v81, v208 dst_sel:DWORD dst_unused:UNUSED_PAD src0_sel:WORD_1 src1_sel:DWORD
	v_add3_u32 v80, v80, v83, s7
	s_add_u32 s8, s16, s8
	v_add3_u32 v81, v81, v82, s7
	v_lshrrev_b32_e32 v80, 16, v80
	s_addc_u32 s9, s17, s9
	v_and_or_b32 v82, v81, s11, v80
	v_lshl_add_u64 v[80:81], s[8:9], 0, v[194:195]
	s_add_i32 s8, s24, s19
	s_cmpk_gt_i32 s8, 0x3fff
	s_cselect_b32 s26, s6, s8
	s_cselect_b32 s8, s33, 0
	s_add_i32 s27, s8, s25
	v_mov_b32_e32 v203, v195
	s_cmp_gt_i32 s18, 7
	v_lshl_add_u64 v[80:81], v[80:81], 0, v[202:203]
	s_cselect_b64 s[16:17], -1, 0
	s_mov_b32 s22, s25
	s_mov_b32 s8, s24
	global_store_dword v[80:81], v82, off
	s_branch .LBB0_621
